# GEMM mainloops: one static priority raise per iteration for waves 4-7 instead of per-segment setprio toggling
# speedup vs baseline: 1.0122x; 1.0122x over previous
; #define PG8_STAGE(bufoff, gbase, voff) do { _Pragma("unroll") for (int _i = 0; _i < 2; ++_i) \
;         __builtin_amdgcn_global_load_lds((const unsigned*)((const char*)(gbase) + (voff)[_i]), (LAS unsigned*)(lds + (bufoff) + ldsw + _i * 8192), 16, 0, 0); } while (0)
; #define PG8_LDA(dst, b, h) do { _Pragma("unroll") for (int m = 0; m < 4; ++m) _Pragma("unroll") for (int k = 0; k < 2; ++k) dst[m][k] = *(const LAS bf16x8*)(lds + PG8_SA(b, h) + aoff + m * 2048 + k * 1024); } while (0)
; #define PG8_LDB(dst, b, h) do { _Pragma("unroll") for (int n = 0; n < 2; ++n) _Pragma("unroll") for (int k = 0; k < 2; ++k) dst[n][k] = *(const LAS bf16x8*)(lds + PG8_SB(b, h) + boff + n * 2048 + k * 1024); } while (0)
; #define PG8_MMA(ai, bj, At, Bt) do { __builtin_amdgcn_s_setprio(1); _Pragma("unroll") for (int m = 0; m < 4; ++m) _Pragma("unroll") for (int n = 0; n < 2; ++n) _Pragma("unroll") for (int k = 0; k < 2; ++k) \
;         acc[ai][bj][m][n] = __builtin_amdgcn_mfma_f32_16x16x32_bf16(Bt[n][k], At[m][k], acc[ai][bj][m][n], 0, 0, 0); __builtin_amdgcn_s_setprio(0); } while (0)
; #define PG8_WAIT_L(n) asm volatile("s_waitcnt lgkmcnt(" #n ")" ::: "memory")
; #define PG8_BAR __builtin_amdgcn_s_barrier()
; #define PG8_SCHED __builtin_amdgcn_sched_barrier(0)
; template <class Epi>
; DEV void gemm_phase(LAS unsigned char* lds, const int tid, const Gemm g, const StaticOrder& S, const Epi& E) {
;     ...
;         for (int t = 0; t < nt; t += 2) {
;             const bool last = (t == nt - 2);
;             const char* a1 = cA + (size_t)(t + 1) * kstep;
;             const char* a2 = last ? nA : cA + (size_t)(t + 2) * kstep; const char* b2 = last ? nB : cB + (size_t)(t + 2) * kstep;
;             const char* a3 = a2 + kstep; const char* b3 = b2 + kstep;
;             PG8_LDB(B0, 0, 0); PG8_SCHED; PG8_LDA(At, 0, 0); PG8_STAGE(PG8_SA(1, 1), a1 + hstep, voffA);
;             PG8_WAIT_L(8); PG8_BAR; PG8_WAIT_L(0); PG8_MMA(0, 0, At, B0); PG8_BAR; PG8_SCHED;
;             PG8_LDB(B1, 0, 1); PG8_STAGE(PG8_SB(0, 0), b2, voffB);
;             PG8_BAR; PG8_WAIT_L(0); PG8_MMA(0, 1, At, B1); PG8_BAR;
;             PG8_LDA(At, 0, 1); PG8_STAGE(PG8_SA(0, 0), a2, voffA);
;             PG8_BAR; PG8_WAIT_L(0); PG8_MMA(1, 0, At, B0); PG8_BAR; PG8_SCHED;
.LBB0_239:
	v_readfirstlane_b32 s100, v188
	s_bitcmp1_b32 s100, 8
	s_cbranch_scc0 .Lprio_skip_0
	s_setprio 1
.Lprio_skip_0:
	s_add_u32 s6, s20, 0xfffc0080
	s_addc_u32 s7, s21, -1
	s_add_i32 s38, 0, 0x10000
	v_add_u32_e32 v166, s38, v1
	ds_read_b128 v[152:155], v166
	ds_read_b128 v[158:161], v166 offset:1024
	ds_read_b128 v[162:165], v166 offset:2048
	ds_read_b128 v[166:169], v166 offset:3072
	s_cmp_eq_u32 s37, 12
	s_cselect_b32 s23, s17, s7
	s_cselect_b32 s22, s16, s6
	s_cselect_b32 s7, s5, s36
	s_cselect_b32 s6, s34, s35
	v_lshl_add_u64 v[186:187], s[20:21], 0, v[138:139]
	s_add_i32 m0, s1, 0xc000
	ds_read_b128 v[170:173], v157
	ds_read_b128 v[174:177], v157 offset:1024
	ds_read_b128 v[178:181], v157 offset:2048
	ds_read_b128 v[182:185], v157 offset:3072
	ds_read_b128 v[198:201], v157 offset:4096
	ds_read_b128 v[202:205], v157 offset:5120
	ds_read_b128 v[206:209], v157 offset:6144
	ds_read_b128 v[210:213], v157 offset:7168
	global_load_lds_dwordx4 v[186:187], off
	v_lshl_add_u64 v[186:187], s[20:21], 0, v[150:151]
	s_add_i32 m0, s1, 0xe000
	s_nop 0
	global_load_lds_dwordx4 v[186:187], off
	s_waitcnt lgkmcnt(8)
	s_barrier
	s_waitcnt lgkmcnt(0)
	s_waitcnt lgkmcnt(0)
	v_mfma_f32_16x16x32_bf16 v[126:129], v[152:155], v[170:173], v[126:129]
	v_mfma_f32_16x16x32_bf16 v[122:125], v[162:165], v[170:173], v[122:125]
	v_mfma_f32_16x16x32_bf16 v[118:121], v[152:155], v[178:181], v[118:121]
	v_mfma_f32_16x16x32_bf16 v[110:113], v[162:165], v[178:181], v[110:113]
	v_mfma_f32_16x16x32_bf16 v[102:105], v[152:155], v[198:201], v[102:105]
	v_mfma_f32_16x16x32_bf16 v[94:97], v[162:165], v[198:201], v[94:97]
	v_mfma_f32_16x16x32_bf16 v[86:89], v[152:155], v[206:209], v[86:89]
	v_mfma_f32_16x16x32_bf16 v[78:81], v[162:165], v[206:209], v[78:81]
	v_mfma_f32_16x16x32_bf16 v[126:129], v[158:161], v[174:177], v[126:129]
	v_mfma_f32_16x16x32_bf16 v[122:125], v[166:169], v[174:177], v[122:125]
	v_mfma_f32_16x16x32_bf16 v[118:121], v[158:161], v[182:185], v[118:121]
	v_mfma_f32_16x16x32_bf16 v[110:113], v[166:169], v[182:185], v[110:113]
	v_mfma_f32_16x16x32_bf16 v[102:105], v[158:161], v[202:205], v[102:105]
	v_mfma_f32_16x16x32_bf16 v[94:97], v[166:169], v[202:205], v[94:97]
	v_mfma_f32_16x16x32_bf16 v[86:89], v[158:161], v[210:213], v[86:89]
	v_mfma_f32_16x16x32_bf16 v[78:81], v[166:169], v[210:213], v[78:81]
	s_barrier
	s_add_i32 s40, 0, 0x14000
	v_add_u32_e32 v186, s40, v1
	s_add_i32 s38, s38, s24
	ds_read_b128 v[214:217], v186
	ds_read_b128 v[218:221], v186 offset:1024
	ds_read_b128 v[222:225], v186 offset:2048
	ds_read_b128 v[226:229], v186 offset:3072
	v_lshl_add_u64 v[186:187], s[6:7], 0, v[132:133]
	s_mov_b32 m0, s38
	v_lshl_add_u64 v[230:231], s[6:7], 0, v[136:137]
	global_load_lds_dwordx4 v[186:187], off
	s_add_i32 m0, s38, 0x2000
	s_nop 0
	global_load_lds_dwordx4 v[230:231], off
	s_barrier
	s_waitcnt lgkmcnt(0)
	s_waitcnt lgkmcnt(0)
	v_mfma_f32_16x16x32_bf16 v[114:117], v[214:217], v[170:173], v[114:117]
	v_mfma_f32_16x16x32_bf16 v[106:109], v[222:225], v[170:173], v[106:109]
	v_mfma_f32_16x16x32_bf16 v[98:101], v[214:217], v[178:181], v[98:101]
	v_mfma_f32_16x16x32_bf16 v[90:93], v[222:225], v[178:181], v[90:93]
	v_mfma_f32_16x16x32_bf16 v[82:85], v[214:217], v[198:201], v[82:85]
	v_mfma_f32_16x16x32_bf16 v[74:77], v[222:225], v[198:201], v[74:77]
	v_mfma_f32_16x16x32_bf16 v[70:73], v[214:217], v[206:209], v[70:73]
	v_mfma_f32_16x16x32_bf16 v[66:69], v[222:225], v[206:209], v[66:69]
	v_mfma_f32_16x16x32_bf16 v[114:117], v[218:221], v[174:177], v[114:117]
	v_mfma_f32_16x16x32_bf16 v[106:109], v[226:229], v[174:177], v[106:109]
	v_mfma_f32_16x16x32_bf16 v[98:101], v[218:221], v[182:185], v[98:101]
	v_mfma_f32_16x16x32_bf16 v[90:93], v[226:229], v[182:185], v[90:93]
	v_mfma_f32_16x16x32_bf16 v[82:85], v[218:221], v[202:205], v[82:85]
	v_mfma_f32_16x16x32_bf16 v[74:77], v[226:229], v[202:205], v[74:77]
	v_mfma_f32_16x16x32_bf16 v[70:73], v[218:221], v[210:213], v[70:73]
	v_mfma_f32_16x16x32_bf16 v[66:69], v[226:229], v[210:213], v[66:69]
	s_mov_b32 m0, s1
	v_lshl_add_u64 v[232:233], s[22:23], 0, v[130:131]
	s_barrier
	ds_read_b128 v[170:173], v157 offset:16384
	ds_read_b128 v[174:177], v157 offset:17408
	ds_read_b128 v[178:181], v157 offset:18432
	ds_read_b128 v[182:185], v157 offset:19456
	ds_read_b128 v[198:201], v157 offset:20480
	ds_read_b128 v[202:205], v157 offset:21504
	ds_read_b128 v[206:209], v157 offset:22528
	ds_read_b128 v[210:213], v157 offset:23552
	global_load_lds_dwordx4 v[232:233], off
	v_lshl_add_u64 v[234:235], s[22:23], 0, v[134:135]
	s_mov_b32 m0, s25
	s_nop 0
	global_load_lds_dwordx4 v[234:235], off
	s_barrier
	s_waitcnt lgkmcnt(0)
	s_waitcnt lgkmcnt(0)
	v_mfma_f32_16x16x32_bf16 v[62:65], v[152:155], v[170:173], v[62:65]
	v_mfma_f32_16x16x32_bf16 v[58:61], v[162:165], v[170:173], v[58:61]
	v_mfma_f32_16x16x32_bf16 v[54:57], v[152:155], v[178:181], v[54:57]
	v_mfma_f32_16x16x32_bf16 v[46:49], v[162:165], v[178:181], v[46:49]
	v_mfma_f32_16x16x32_bf16 v[38:41], v[152:155], v[198:201], v[38:41]
	v_mfma_f32_16x16x32_bf16 v[30:33], v[162:165], v[198:201], v[30:33]
	v_mfma_f32_16x16x32_bf16 v[22:25], v[152:155], v[206:209], v[22:25]
	v_mfma_f32_16x16x32_bf16 v[14:17], v[162:165], v[206:209], v[14:17]
	v_mfma_f32_16x16x32_bf16 v[62:65], v[158:161], v[174:177], v[62:65]
	v_mfma_f32_16x16x32_bf16 v[58:61], v[166:169], v[174:177], v[58:61]
	v_mfma_f32_16x16x32_bf16 v[54:57], v[158:161], v[182:185], v[54:57]
	v_mfma_f32_16x16x32_bf16 v[46:49], v[166:169], v[182:185], v[46:49]
	v_mfma_f32_16x16x32_bf16 v[38:41], v[158:161], v[202:205], v[38:41]
	v_mfma_f32_16x16x32_bf16 v[30:33], v[166:169], v[202:205], v[30:33]
	v_mfma_f32_16x16x32_bf16 v[22:25], v[158:161], v[210:213], v[22:25]
	v_mfma_f32_16x16x32_bf16 v[14:17], v[166:169], v[210:213], v[14:17]
	s_barrier
; #define PG8_STAGE(bufoff, gbase, voff) do { _Pragma("unroll") for (int _i = 0; _i < 2; ++_i) \
;         __builtin_amdgcn_global_load_lds((const unsigned*)((const char*)(gbase) + (voff)[_i]), (LAS unsigned*)(lds + (bufoff) + ldsw + _i * 8192), 16, 0, 0); } while (0)
; #define PG8_LDA(dst, b, h) do { _Pragma("unroll") for (int m = 0; m < 4; ++m) _Pragma("unroll") for (int k = 0; k < 2; ++k) dst[m][k] = *(const LAS bf16x8*)(lds + PG8_SA(b, h) + aoff + m * 2048 + k * 1024); } while (0)
; #define PG8_LDB(dst, b, h) do { _Pragma("unroll") for (int n = 0; n < 2; ++n) _Pragma("unroll") for (int k = 0; k < 2; ++k) dst[n][k] = *(const LAS bf16x8*)(lds + PG8_SB(b, h) + boff + n * 2048 + k * 1024); } while (0)
; #define PG8_MMA(ai, bj, At, Bt) do { __builtin_amdgcn_s_setprio(1); _Pragma("unroll") for (int m = 0; m < 4; ++m) _Pragma("unroll") for (int n = 0; n < 2; ++n) _Pragma("unroll") for (int k = 0; k < 2; ++k) \
;         acc[ai][bj][m][n] = __builtin_amdgcn_mfma_f32_16x16x32_bf16(Bt[n][k], At[m][k], acc[ai][bj][m][n], 0, 0, 0); __builtin_amdgcn_s_setprio(0); } while (0)
; #define PG8_WAIT_V(n) asm volatile("s_waitcnt vmcnt(" #n ")" ::: "memory")
; #define PG8_WAIT_L(n) asm volatile("s_waitcnt lgkmcnt(" #n ")" ::: "memory")
; #define PG8_BAR __builtin_amdgcn_s_barrier()
; #define PG8_SCHED __builtin_amdgcn_sched_barrier(0)
; template <class Epi>
; DEV void gemm_phase(LAS unsigned char* lds, const int tid, const Gemm g, const StaticOrder& S, const Epi& E) {
;     ...
;             PG8_BAR; PG8_WAIT_L(0); PG8_MMA(1, 0, At, B0); PG8_BAR; PG8_SCHED;
;             PG8_STAGE(PG8_SB(0, 1), b2 + hstep, voffB);
;             PG8_WAIT_V(6); PG8_BAR; PG8_MMA(1, 1, At, B1); PG8_BAR;
;             PG8_LDB(B0, 1, 0); PG8_SCHED; PG8_LDA(At, 1, 0); PG8_STAGE(PG8_SA(0, 1), a2 + hstep, voffA);
;             PG8_WAIT_L(8); PG8_BAR; PG8_WAIT_L(0); PG8_MMA(0, 0, At, B0); PG8_BAR; PG8_SCHED;
;             PG8_LDB(B1, 1, 1); PG8_STAGE(PG8_SB(1, 0), b3, voffB);
;             PG8_BAR; PG8_WAIT_L(0); PG8_MMA(0, 1, At, B1); PG8_BAR;
;             PG8_LDA(At, 1, 1); PG8_STAGE(PG8_SA(1, 0), a3, voffA);
;             PG8_BAR; PG8_WAIT_L(0); PG8_MMA(1, 0, At, B0); PG8_BAR; PG8_SCHED;
	s_add_u32 s38, s6, 0x40000
	s_addc_u32 s39, s7, 0
	s_add_i32 s40, s40, s24
	v_lshl_add_u64 v[152:153], s[38:39], 0, v[132:133]
	s_mov_b32 m0, s40
	s_nop 0
	global_load_lds_dwordx4 v[152:153], off
	v_lshl_add_u64 v[152:153], s[38:39], 0, v[136:137]
	s_add_i32 m0, s40, 0x2000
	s_nop 0
	global_load_lds_dwordx4 v[152:153], off
	s_waitcnt vmcnt(6)
	s_barrier
	v_mfma_f32_16x16x32_bf16 v[50:53], v[214:217], v[170:173], v[50:53]
	v_mfma_f32_16x16x32_bf16 v[42:45], v[222:225], v[170:173], v[42:45]
	v_mfma_f32_16x16x32_bf16 v[34:37], v[214:217], v[178:181], v[34:37]
	v_mfma_f32_16x16x32_bf16 v[26:29], v[222:225], v[178:181], v[26:29]
	v_mfma_f32_16x16x32_bf16 v[18:21], v[214:217], v[198:201], v[18:21]
	v_mfma_f32_16x16x32_bf16 v[10:13], v[222:225], v[198:201], v[10:13]
	v_mfma_f32_16x16x32_bf16 v[6:9], v[214:217], v[206:209], v[6:9]
	v_mfma_f32_16x16x32_bf16 v[2:5], v[222:225], v[206:209], v[2:5]
	v_mfma_f32_16x16x32_bf16 v[50:53], v[218:221], v[174:177], v[50:53]
	v_mfma_f32_16x16x32_bf16 v[42:45], v[226:229], v[174:177], v[42:45]
	v_mfma_f32_16x16x32_bf16 v[34:37], v[218:221], v[182:185], v[34:37]
	v_mfma_f32_16x16x32_bf16 v[26:29], v[226:229], v[182:185], v[26:29]
	v_mfma_f32_16x16x32_bf16 v[18:21], v[218:221], v[202:205], v[18:21]
	v_mfma_f32_16x16x32_bf16 v[10:13], v[226:229], v[202:205], v[10:13]
	v_mfma_f32_16x16x32_bf16 v[6:9], v[218:221], v[210:213], v[6:9]
	v_mfma_f32_16x16x32_bf16 v[2:5], v[226:229], v[210:213], v[2:5]
	s_add_i32 s38, 0, 0x18000
	v_add_u32_e32 v166, s38, v1
	s_barrier
	ds_read_b128 v[152:155], v166
	ds_read_b128 v[158:161], v166 offset:1024
	ds_read_b128 v[162:165], v166 offset:2048
	ds_read_b128 v[166:169], v166 offset:3072
	s_add_u32 s22, s22, 0x40000
	s_addc_u32 s23, s23, 0
	s_mov_b32 m0, s26
	v_lshl_add_u64 v[214:215], s[22:23], 0, v[130:131]
	ds_read_b128 v[170:173], v157 offset:32768
	ds_read_b128 v[174:177], v157 offset:33792
	ds_read_b128 v[178:181], v157 offset:34816
	ds_read_b128 v[182:185], v157 offset:35840
	ds_read_b128 v[198:201], v157 offset:36864
	ds_read_b128 v[202:205], v157 offset:37888
	ds_read_b128 v[206:209], v157 offset:38912
	ds_read_b128 v[210:213], v157 offset:39936
	global_load_lds_dwordx4 v[214:215], off
	v_lshl_add_u64 v[214:215], s[22:23], 0, v[134:135]
	s_mov_b32 m0, s27
	s_nop 0
	global_load_lds_dwordx4 v[214:215], off
	s_waitcnt lgkmcnt(8)
	s_barrier
	s_waitcnt lgkmcnt(0)
	s_waitcnt lgkmcnt(0)
	v_mfma_f32_16x16x32_bf16 v[126:129], v[152:155], v[170:173], v[126:129]
	v_mfma_f32_16x16x32_bf16 v[122:125], v[162:165], v[170:173], v[122:125]
	v_mfma_f32_16x16x32_bf16 v[118:121], v[152:155], v[178:181], v[118:121]
	v_mfma_f32_16x16x32_bf16 v[110:113], v[162:165], v[178:181], v[110:113]
	v_mfma_f32_16x16x32_bf16 v[102:105], v[152:155], v[198:201], v[102:105]
	v_mfma_f32_16x16x32_bf16 v[94:97], v[162:165], v[198:201], v[94:97]
	v_mfma_f32_16x16x32_bf16 v[86:89], v[152:155], v[206:209], v[86:89]
	v_mfma_f32_16x16x32_bf16 v[78:81], v[162:165], v[206:209], v[78:81]
	v_mfma_f32_16x16x32_bf16 v[126:129], v[158:161], v[174:177], v[126:129]
	v_mfma_f32_16x16x32_bf16 v[122:125], v[166:169], v[174:177], v[122:125]
	v_mfma_f32_16x16x32_bf16 v[118:121], v[158:161], v[182:185], v[118:121]
	v_mfma_f32_16x16x32_bf16 v[110:113], v[166:169], v[182:185], v[110:113]
	v_mfma_f32_16x16x32_bf16 v[102:105], v[158:161], v[202:205], v[102:105]
	v_mfma_f32_16x16x32_bf16 v[94:97], v[166:169], v[202:205], v[94:97]
	v_mfma_f32_16x16x32_bf16 v[86:89], v[158:161], v[210:213], v[86:89]
	v_mfma_f32_16x16x32_bf16 v[78:81], v[166:169], v[210:213], v[78:81]
	s_barrier
	s_add_i32 s22, 0, 0x1c000
	s_add_i32 s23, s38, s24
	v_add_u32_e32 v226, s22, v1
	v_lshl_add_u64 v[186:187], v[186:187], 0, s[10:11]
	s_mov_b32 m0, s23
	ds_read_b128 v[214:217], v226
	ds_read_b128 v[218:221], v226 offset:1024
	ds_read_b128 v[222:225], v226 offset:2048
	ds_read_b128 v[226:229], v226 offset:3072
	global_load_lds_dwordx4 v[186:187], off
	v_lshl_add_u64 v[186:187], v[230:231], 0, s[10:11]
	s_add_i32 m0, s23, 0x2000
	s_nop 0
	global_load_lds_dwordx4 v[186:187], off
	s_barrier
	s_waitcnt lgkmcnt(0)
	s_waitcnt lgkmcnt(0)
	v_mfma_f32_16x16x32_bf16 v[114:117], v[214:217], v[170:173], v[114:117]
	v_mfma_f32_16x16x32_bf16 v[106:109], v[222:225], v[170:173], v[106:109]
	v_mfma_f32_16x16x32_bf16 v[98:101], v[214:217], v[178:181], v[98:101]
	v_mfma_f32_16x16x32_bf16 v[90:93], v[222:225], v[178:181], v[90:93]
	v_mfma_f32_16x16x32_bf16 v[82:85], v[214:217], v[198:201], v[82:85]
	v_mfma_f32_16x16x32_bf16 v[74:77], v[222:225], v[198:201], v[74:77]
	v_mfma_f32_16x16x32_bf16 v[70:73], v[214:217], v[206:209], v[70:73]
	v_mfma_f32_16x16x32_bf16 v[66:69], v[222:225], v[206:209], v[66:69]
	v_mfma_f32_16x16x32_bf16 v[114:117], v[218:221], v[174:177], v[114:117]
	v_mfma_f32_16x16x32_bf16 v[106:109], v[226:229], v[174:177], v[106:109]
	v_mfma_f32_16x16x32_bf16 v[98:101], v[218:221], v[182:185], v[98:101]
	v_mfma_f32_16x16x32_bf16 v[90:93], v[226:229], v[182:185], v[90:93]
	v_mfma_f32_16x16x32_bf16 v[82:85], v[218:221], v[202:205], v[82:85]
	v_mfma_f32_16x16x32_bf16 v[74:77], v[226:229], v[202:205], v[74:77]
	v_mfma_f32_16x16x32_bf16 v[70:73], v[218:221], v[210:213], v[70:73]
	v_mfma_f32_16x16x32_bf16 v[66:69], v[226:229], v[210:213], v[66:69]
	s_mov_b32 m0, s28
	v_lshl_add_u64 v[186:187], v[232:233], 0, s[10:11]
	s_barrier
	ds_read_b128 v[170:173], v157 offset:49152
	ds_read_b128 v[174:177], v157 offset:50176
	ds_read_b128 v[178:181], v157 offset:51200
	ds_read_b128 v[182:185], v157 offset:52224
	ds_read_b128 v[198:201], v157 offset:53248
	ds_read_b128 v[202:205], v157 offset:54272
	ds_read_b128 v[206:209], v157 offset:55296
	ds_read_b128 v[210:213], v157 offset:56320
	global_load_lds_dwordx4 v[186:187], off
	v_lshl_add_u64 v[186:187], v[234:235], 0, s[10:11]
	s_mov_b32 m0, s29
	s_nop 0
	global_load_lds_dwordx4 v[186:187], off
	s_barrier
; #define PG8_STAGE(bufoff, gbase, voff) do { _Pragma("unroll") for (int _i = 0; _i < 2; ++_i) \
;         __builtin_amdgcn_global_load_lds((const unsigned*)((const char*)(gbase) + (voff)[_i]), (LAS unsigned*)(lds + (bufoff) + ldsw + _i * 8192), 16, 0, 0); } while (0)
; #define PG8_MMA(ai, bj, At, Bt) do { __builtin_amdgcn_s_setprio(1); _Pragma("unroll") for (int m = 0; m < 4; ++m) _Pragma("unroll") for (int n = 0; n < 2; ++n) _Pragma("unroll") for (int k = 0; k < 2; ++k) \
;         acc[ai][bj][m][n] = __builtin_amdgcn_mfma_f32_16x16x32_bf16(Bt[n][k], At[m][k], acc[ai][bj][m][n], 0, 0, 0); __builtin_amdgcn_s_setprio(0); } while (0)
; #define PG8_WAIT_V(n) asm volatile("s_waitcnt vmcnt(" #n ")" ::: "memory")
; #define PG8_WAIT_L(n) asm volatile("s_waitcnt lgkmcnt(" #n ")" ::: "memory")
; #define PG8_BAR __builtin_amdgcn_s_barrier()
; #define PG8_SCHED __builtin_amdgcn_sched_barrier(0)
; template <class Epi>
; DEV void gemm_phase(LAS unsigned char* lds, const int tid, const Gemm g, const StaticOrder& S, const Epi& E) {
;     ...
;             PG8_BAR; PG8_WAIT_L(0); PG8_MMA(1, 0, At, B0); PG8_BAR; PG8_SCHED;
;             PG8_STAGE(PG8_SB(1, 1), b3 + hstep, voffB);
;             PG8_WAIT_V(6); PG8_BAR; PG8_MMA(1, 1, At, B1); PG8_BAR;
;         }
	s_waitcnt lgkmcnt(0)
	s_waitcnt lgkmcnt(0)
	v_mfma_f32_16x16x32_bf16 v[62:65], v[152:155], v[170:173], v[62:65]
	v_mfma_f32_16x16x32_bf16 v[58:61], v[162:165], v[170:173], v[58:61]
	v_mfma_f32_16x16x32_bf16 v[54:57], v[152:155], v[178:181], v[54:57]
	v_mfma_f32_16x16x32_bf16 v[46:49], v[162:165], v[178:181], v[46:49]
	v_mfma_f32_16x16x32_bf16 v[38:41], v[152:155], v[198:201], v[38:41]
	v_mfma_f32_16x16x32_bf16 v[30:33], v[162:165], v[198:201], v[30:33]
	v_mfma_f32_16x16x32_bf16 v[22:25], v[152:155], v[206:209], v[22:25]
	v_mfma_f32_16x16x32_bf16 v[14:17], v[162:165], v[206:209], v[14:17]
	v_mfma_f32_16x16x32_bf16 v[62:65], v[158:161], v[174:177], v[62:65]
	v_mfma_f32_16x16x32_bf16 v[58:61], v[166:169], v[174:177], v[58:61]
	v_mfma_f32_16x16x32_bf16 v[54:57], v[158:161], v[182:185], v[54:57]
	v_mfma_f32_16x16x32_bf16 v[46:49], v[166:169], v[182:185], v[46:49]
	v_mfma_f32_16x16x32_bf16 v[38:41], v[158:161], v[202:205], v[38:41]
	v_mfma_f32_16x16x32_bf16 v[30:33], v[166:169], v[202:205], v[30:33]
	v_mfma_f32_16x16x32_bf16 v[22:25], v[158:161], v[210:213], v[22:25]
	v_mfma_f32_16x16x32_bf16 v[14:17], v[166:169], v[210:213], v[14:17]
	s_barrier
	s_add_u32 s6, s6, 0x40080
	s_addc_u32 s7, s7, 0
	s_add_i32 s22, s22, s24
	v_lshl_add_u64 v[152:153], s[6:7], 0, v[132:133]
	s_mov_b32 m0, s22
	s_nop 0
	global_load_lds_dwordx4 v[152:153], off
	v_lshl_add_u64 v[152:153], s[6:7], 0, v[136:137]
	s_add_i32 m0, s22, 0x2000
	s_nop 0
	global_load_lds_dwordx4 v[152:153], off
	s_waitcnt vmcnt(6)
	s_barrier
	v_mfma_f32_16x16x32_bf16 v[50:53], v[214:217], v[170:173], v[50:53]
	v_mfma_f32_16x16x32_bf16 v[42:45], v[222:225], v[170:173], v[42:45]
	v_mfma_f32_16x16x32_bf16 v[34:37], v[214:217], v[178:181], v[34:37]
	v_mfma_f32_16x16x32_bf16 v[26:29], v[222:225], v[178:181], v[26:29]
	v_mfma_f32_16x16x32_bf16 v[18:21], v[214:217], v[198:201], v[18:21]
	v_mfma_f32_16x16x32_bf16 v[10:13], v[222:225], v[198:201], v[10:13]
	v_mfma_f32_16x16x32_bf16 v[6:9], v[214:217], v[206:209], v[6:9]
	v_mfma_f32_16x16x32_bf16 v[2:5], v[222:225], v[206:209], v[2:5]
	v_mfma_f32_16x16x32_bf16 v[50:53], v[218:221], v[174:177], v[50:53]
	v_mfma_f32_16x16x32_bf16 v[42:45], v[226:229], v[174:177], v[42:45]
	v_mfma_f32_16x16x32_bf16 v[34:37], v[218:221], v[182:185], v[34:37]
	v_mfma_f32_16x16x32_bf16 v[26:29], v[226:229], v[182:185], v[26:29]
	v_mfma_f32_16x16x32_bf16 v[18:21], v[218:221], v[202:205], v[18:21]
	v_mfma_f32_16x16x32_bf16 v[10:13], v[226:229], v[202:205], v[10:13]
	v_mfma_f32_16x16x32_bf16 v[6:9], v[218:221], v[210:213], v[6:9]
	v_mfma_f32_16x16x32_bf16 v[2:5], v[226:229], v[210:213], v[2:5]
	s_setprio 0
	s_add_i32 s37, s37, 2
	s_add_u32 s20, s20, 0x100
	s_addc_u32 s21, s21, 0
	s_add_u32 s35, s35, 0x100
	s_addc_u32 s36, s36, 0
	s_cmp_gt_u32 s37, 13
	s_barrier
	s_cbranch_scc0 .LBB0_239
; DEV unsigned cvt_pk_bf16(float lo, float hi) { unsigned r; asm volatile("v_cvt_pk_bf16_f32 %0, %1, %2" : "=v"(r) : "v"(lo), "v"(hi)); return r; }
; #define PG8_WAIT_V(n) asm volatile("s_waitcnt vmcnt(" #n ")" ::: "memory")
; #define PG8_BAR __builtin_amdgcn_s_barrier()
;     DEV void operator()(const f32x4 (&acc)[2][2][4][2], const Unit& u, int wr, int wc, int fr, int fq) const {
;         const int row0 = prow(u.pm) + wr * 64 + fr; const int col0 = u.pn * BM + wc * 32 + 8 * fq;
; #pragma unroll
;         for (int ai = 0; ai < 2; ++ai)
; #pragma unroll
;             for (int m = 0; m < 4; ++m) { bf16_t* rowp = O + (size_t)(row0 + ai * HALF + m * 16) * ldc + col0;
; #pragma unroll
;                 for (int bj = 0; bj < 2; ++bj) { const f32x4 v0 = acc[ai][bj][m][0], v1 = acc[ai][bj][m][1];
;                     u32x4 w; w.x = cvt_pk_bf16(v0[0], v0[1]); w.y = cvt_pk_bf16(v0[2], v0[3]); w.z = cvt_pk_bf16(v1[0], v1[1]); w.w = cvt_pk_bf16(v1[2], v1[3]);
;                     *(u32x4*)(rowp + bj * HALF) = w; } }
;     }
; template <class Epi>
; DEV void gemm_phase(LAS unsigned char* lds, const int tid, const Gemm g, const StaticOrder& S, const Epi& E) {
;     ...
;         E(acc, cur, wr, wc, fr, fq);
;         if (!has_next) break;
; #pragma unroll
;         for (int a = 0; a < 2; ++a)
; #pragma unroll
;             for (int b = 0; b < 2; ++b)
; #pragma unroll
;                 for (int m = 0; m < 4; ++m)
; #pragma unroll
;                     for (int n = 0; n < 2; ++n) acc[a][b][m][n] = (f32x4){0.f, 0.f, 0.f, 0.f};
;         cur = nxt; cA = nA; cB = nB; ++ui;
;     }
;     PG8_WAIT_V(0);
;     if (wr == 0) PG8_BAR;
;     PG8_BAR;
	s_lshl_b32 s6, s31, 2
	s_lshl_b32 s5, s31, 8
	s_and_b32 s6, s6, 0xffffff00
	s_add_i32 s6, s6, s5
	v_lshl_or_b32 v154, s0, 8, v156
	v_add_u32_e32 v160, s6, v141
	v_ashrrev_i32_e32 v155, 31, v154
	v_mov_b64_e32 v[152:153], s[78:79]
	v_mad_i64_i32 v[158:159], s[6:7], v160, s53, v[152:153]
	v_lshlrev_b64 v[154:155], 1, v[154:155]
	v_lshl_add_u64 v[158:159], v[158:159], 0, v[154:155]
	v_cvt_pk_bf16_f32 v126, v126, v127
	v_cvt_pk_bf16_f32 v127, v128, v129
	v_cvt_pk_bf16_f32 v128, v122, v123
	v_cvt_pk_bf16_f32 v129, v124, v125
	global_store_dwordx4 v[158:159], v[126:129], off
	v_cvt_pk_bf16_f32 v114, v114, v115
	v_cvt_pk_bf16_f32 v115, v116, v117
	v_cvt_pk_bf16_f32 v116, v106, v107
	v_or_b32_e32 v106, 16, v160
	v_mad_i64_i32 v[106:107], s[6:7], v106, s53, v[152:153]
	v_cvt_pk_bf16_f32 v117, v108, v109
	global_store_dwordx4 v[158:159], v[114:117], off offset:256
	s_and_b64 vcc, exec, s[8:9]
	s_mov_b32 s0, s4
	v_lshl_add_u64 v[114:115], v[106:107], 0, v[154:155]
	v_cvt_pk_bf16_f32 v106, v118, v119
	v_cvt_pk_bf16_f32 v107, v120, v121
	v_cvt_pk_bf16_f32 v108, v110, v111
	v_cvt_pk_bf16_f32 v109, v112, v113
	global_store_dwordx4 v[114:115], v[106:109], off
	v_cvt_pk_bf16_f32 v98, v98, v99
	v_cvt_pk_bf16_f32 v99, v100, v101
	v_cvt_pk_bf16_f32 v100, v90, v91
	v_or_b32_e32 v90, 32, v160
	v_mad_i64_i32 v[90:91], s[6:7], v90, s53, v[152:153]
	v_cvt_pk_bf16_f32 v101, v92, v93
	global_store_dwordx4 v[114:115], v[98:101], off offset:256
	s_mov_b32 s31, s33
	s_mov_b32 s34, s4
	v_lshl_add_u64 v[98:99], v[90:91], 0, v[154:155]
	v_cvt_pk_bf16_f32 v90, v102, v103
	v_cvt_pk_bf16_f32 v91, v104, v105
	v_cvt_pk_bf16_f32 v92, v94, v95
	v_cvt_pk_bf16_f32 v93, v96, v97
	global_store_dwordx4 v[98:99], v[90:93], off
	v_cvt_pk_bf16_f32 v82, v82, v83
	v_cvt_pk_bf16_f32 v83, v84, v85
	v_cvt_pk_bf16_f32 v84, v74, v75
	v_or_b32_e32 v74, 48, v160
	v_mad_i64_i32 v[74:75], s[6:7], v74, s53, v[152:153]
	v_cvt_pk_bf16_f32 v85, v76, v77
	global_store_dwordx4 v[98:99], v[82:85], off offset:256
	s_mov_b32 s35, s33
	s_mov_b64 s[20:21], s[16:17]
	v_lshl_add_u64 v[82:83], v[74:75], 0, v[154:155]
	v_cvt_pk_bf16_f32 v74, v86, v87
	v_cvt_pk_bf16_f32 v75, v88, v89
	v_cvt_pk_bf16_f32 v76, v78, v79
	v_cvt_pk_bf16_f32 v77, v80, v81
	global_store_dwordx4 v[82:83], v[74:77], off
	v_cvt_pk_bf16_f32 v70, v70, v71
	v_cvt_pk_bf16_f32 v71, v72, v73
	v_cvt_pk_bf16_f32 v72, v66, v67
	v_add_u32_e32 v66, 0x80, v160
	v_mad_i64_i32 v[66:67], s[6:7], v66, s53, v[152:153]
	v_lshl_add_u64 v[66:67], v[66:67], 0, v[154:155]
	v_cvt_pk_bf16_f32 v73, v68, v69
	global_store_dwordx4 v[82:83], v[70:73], off offset:256
	v_cvt_pk_bf16_f32 v62, v62, v63
	v_cvt_pk_bf16_f32 v63, v64, v65
	v_cvt_pk_bf16_f32 v64, v58, v59
	v_cvt_pk_bf16_f32 v65, v60, v61
	global_store_dwordx4 v[66:67], v[62:65], off
	v_cvt_pk_bf16_f32 v50, v50, v51
	v_cvt_pk_bf16_f32 v51, v52, v53
	v_cvt_pk_bf16_f32 v52, v42, v43
	v_add_u32_e32 v42, 0x90, v160
	v_mad_i64_i32 v[42:43], s[6:7], v42, s53, v[152:153]
	v_cvt_pk_bf16_f32 v53, v44, v45
	global_store_dwordx4 v[66:67], v[50:53], off offset:256
	s_nop 1
	v_lshl_add_u64 v[50:51], v[42:43], 0, v[154:155]
	v_cvt_pk_bf16_f32 v42, v54, v55
	v_cvt_pk_bf16_f32 v43, v56, v57
	v_cvt_pk_bf16_f32 v44, v46, v47
	v_cvt_pk_bf16_f32 v45, v48, v49
	global_store_dwordx4 v[50:51], v[42:45], off
	v_cvt_pk_bf16_f32 v34, v34, v35
	v_cvt_pk_bf16_f32 v35, v36, v37
	v_cvt_pk_bf16_f32 v36, v26, v27
	v_add_u32_e32 v26, 0xa0, v160
	v_mad_i64_i32 v[26:27], s[6:7], v26, s53, v[152:153]
	v_cvt_pk_bf16_f32 v37, v28, v29
	global_store_dwordx4 v[50:51], v[34:37], off offset:256
	s_nop 1
	v_lshl_add_u64 v[34:35], v[26:27], 0, v[154:155]
	v_cvt_pk_bf16_f32 v26, v38, v39
	v_cvt_pk_bf16_f32 v27, v40, v41
	v_cvt_pk_bf16_f32 v28, v30, v31
	v_cvt_pk_bf16_f32 v29, v32, v33
	global_store_dwordx4 v[34:35], v[26:29], off
	v_cvt_pk_bf16_f32 v18, v18, v19
	v_cvt_pk_bf16_f32 v19, v20, v21
	v_cvt_pk_bf16_f32 v20, v10, v11
	v_add_u32_e32 v10, 0xb0, v160
	v_mad_i64_i32 v[10:11], s[6:7], v10, s53, v[152:153]
	v_cvt_pk_bf16_f32 v21, v12, v13
	global_store_dwordx4 v[34:35], v[18:21], off offset:256
	s_mov_b64 s[6:7], s[18:19]
	s_nop 0
	v_lshl_add_u64 v[18:19], v[10:11], 0, v[154:155]
	v_cvt_pk_bf16_f32 v10, v22, v23
	v_cvt_pk_bf16_f32 v11, v24, v25
	v_cvt_pk_bf16_f32 v12, v14, v15
	v_cvt_pk_bf16_f32 v13, v16, v17
	global_store_dwordx4 v[18:19], v[10:13], off
	v_cvt_pk_bf16_f32 v6, v6, v7
	v_cvt_pk_bf16_f32 v7, v8, v9
	v_cvt_pk_bf16_f32 v8, v2, v3
	v_cvt_pk_bf16_f32 v9, v4, v5
	global_store_dwordx4 v[18:19], v[6:9], off offset:256
	s_cbranch_vccz .LBB0_229
	s_waitcnt vmcnt(0)
	v_readlane_b32 s34, v240, 59
	s_cmpk_gt_u32 s15, 0xff
	v_readlane_b32 s35, v240, 60
	s_cbranch_scc1 .LBB0_243
	s_barrier

; #define PG8_STAGE(bufoff, gbase, voff) do { _Pragma("unroll") for (int _i = 0; _i < 2; ++_i) \
;         __builtin_amdgcn_global_load_lds((const unsigned*)((const char*)(gbase) + (voff)[_i]), (LAS unsigned*)(lds + (bufoff) + ldsw + _i * 8192), 16, 0, 0); } while (0)
; #define PG8_LDA(dst, b, h) do { _Pragma("unroll") for (int m = 0; m < 4; ++m) _Pragma("unroll") for (int k = 0; k < 2; ++k) dst[m][k] = *(const LAS bf16x8*)(lds + PG8_SA(b, h) + aoff + m * 2048 + k * 1024); } while (0)
; #define PG8_LDB(dst, b, h) do { _Pragma("unroll") for (int n = 0; n < 2; ++n) _Pragma("unroll") for (int k = 0; k < 2; ++k) dst[n][k] = *(const LAS bf16x8*)(lds + PG8_SB(b, h) + boff + n * 2048 + k * 1024); } while (0)
; #define PG8_MMA(ai, bj, At, Bt) do { __builtin_amdgcn_s_setprio(1); _Pragma("unroll") for (int m = 0; m < 4; ++m) _Pragma("unroll") for (int n = 0; n < 2; ++n) _Pragma("unroll") for (int k = 0; k < 2; ++k) \
;         acc[ai][bj][m][n] = __builtin_amdgcn_mfma_f32_16x16x32_bf16(Bt[n][k], At[m][k], acc[ai][bj][m][n], 0, 0, 0); __builtin_amdgcn_s_setprio(0); } while (0)
; #define PG8_WAIT_L(n) asm volatile("s_waitcnt lgkmcnt(" #n ")" ::: "memory")
; #define PG8_BAR __builtin_amdgcn_s_barrier()
; #define PG8_SCHED __builtin_amdgcn_sched_barrier(0)
; template <class Epi>
; DEV void gemm_phase(LAS unsigned char* lds, const int tid, const Gemm g, const StaticOrder& S, const Epi& E) {
;     ...
;         for (int t = 0; t < nt; t += 2) {
;             const bool last = (t == nt - 2);
;             const char* a1 = cA + (size_t)(t + 1) * kstep;
;             const char* a2 = last ? nA : cA + (size_t)(t + 2) * kstep; const char* b2 = last ? nB : cB + (size_t)(t + 2) * kstep;
;             const char* a3 = a2 + kstep; const char* b3 = b2 + kstep;
;             PG8_LDB(B0, 0, 0); PG8_SCHED; PG8_LDA(At, 0, 0); PG8_STAGE(PG8_SA(1, 1), a1 + hstep, voffA);
;             PG8_WAIT_L(8); PG8_BAR; PG8_WAIT_L(0); PG8_MMA(0, 0, At, B0); PG8_BAR; PG8_SCHED;
;             PG8_LDB(B1, 0, 1); PG8_STAGE(PG8_SB(0, 0), b2, voffB);
;             PG8_BAR; PG8_WAIT_L(0); PG8_MMA(0, 1, At, B1); PG8_BAR;
;             PG8_LDA(At, 0, 1); PG8_STAGE(PG8_SA(0, 0), a2, voffA);
;             PG8_BAR; PG8_WAIT_L(0); PG8_MMA(1, 0, At, B0); PG8_BAR; PG8_SCHED;
.Lprio_skip_1:
	s_add_u32 s6, s22, 0xfffc0080
	s_addc_u32 s7, s23, -1
	s_add_i32 s40, 0, 0x10000
	v_add_u32_e32 v152, s40, v1
	ds_read_b128 v[156:159], v152
	ds_read_b128 v[160:163], v152 offset:1024
	ds_read_b128 v[164:167], v152 offset:2048
	ds_read_b128 v[168:171], v152 offset:3072
	s_cmp_eq_u32 s39, 12
	s_cselect_b32 s25, s19, s7
	s_cselect_b32 s24, s18, s6
	s_cselect_b32 s7, s3, s38
	s_cselect_b32 s6, s36, s37
	v_lshl_add_u64 v[152:153], s[22:23], 0, v[138:139]
	s_add_i32 m0, s1, 0xc000
	ds_read_b128 v[172:175], v155
	ds_read_b128 v[176:179], v155 offset:1024
	ds_read_b128 v[180:183], v155 offset:2048
	ds_read_b128 v[184:187], v155 offset:3072
	ds_read_b128 v[198:201], v155 offset:4096
	ds_read_b128 v[202:205], v155 offset:5120
	ds_read_b128 v[206:209], v155 offset:6144
	ds_read_b128 v[210:213], v155 offset:7168
	global_load_lds_dwordx4 v[152:153], off
	v_lshl_add_u64 v[152:153], s[22:23], 0, v[150:151]
	s_add_i32 m0, s1, 0xe000
	s_nop 0
	global_load_lds_dwordx4 v[152:153], off
	s_waitcnt lgkmcnt(8)
	s_barrier
	s_waitcnt lgkmcnt(0)
	s_waitcnt lgkmcnt(0)
	v_mfma_f32_16x16x32_bf16 v[126:129], v[156:159], v[172:175], v[126:129]
	v_mfma_f32_16x16x32_bf16 v[122:125], v[164:167], v[172:175], v[122:125]
	v_mfma_f32_16x16x32_bf16 v[118:121], v[156:159], v[180:183], v[118:121]
	v_mfma_f32_16x16x32_bf16 v[110:113], v[164:167], v[180:183], v[110:113]
	v_mfma_f32_16x16x32_bf16 v[102:105], v[156:159], v[198:201], v[102:105]
	v_mfma_f32_16x16x32_bf16 v[94:97], v[164:167], v[198:201], v[94:97]
	v_mfma_f32_16x16x32_bf16 v[86:89], v[156:159], v[206:209], v[86:89]
	v_mfma_f32_16x16x32_bf16 v[78:81], v[164:167], v[206:209], v[78:81]
	v_mfma_f32_16x16x32_bf16 v[126:129], v[160:163], v[176:179], v[126:129]
	v_mfma_f32_16x16x32_bf16 v[122:125], v[168:171], v[176:179], v[122:125]
	v_mfma_f32_16x16x32_bf16 v[118:121], v[160:163], v[184:187], v[118:121]
	v_mfma_f32_16x16x32_bf16 v[110:113], v[168:171], v[184:187], v[110:113]
	v_mfma_f32_16x16x32_bf16 v[102:105], v[160:163], v[202:205], v[102:105]
	v_mfma_f32_16x16x32_bf16 v[94:97], v[168:171], v[202:205], v[94:97]
	v_mfma_f32_16x16x32_bf16 v[86:89], v[160:163], v[210:213], v[86:89]
	v_mfma_f32_16x16x32_bf16 v[78:81], v[168:171], v[210:213], v[78:81]
	s_barrier
	s_add_i32 s42, 0, 0x14000
	v_add_u32_e32 v152, s42, v1
	s_add_i32 s40, s40, s26
	ds_read_b128 v[214:217], v152
	ds_read_b128 v[218:221], v152 offset:1024
	ds_read_b128 v[222:225], v152 offset:2048
	ds_read_b128 v[226:229], v152 offset:3072
	v_lshl_add_u64 v[152:153], s[6:7], 0, v[132:133]
	s_mov_b32 m0, s40
	v_lshl_add_u64 v[230:231], s[6:7], 0, v[136:137]
	global_load_lds_dwordx4 v[152:153], off
	s_add_i32 m0, s40, 0x2000
	s_nop 0
	global_load_lds_dwordx4 v[230:231], off
	s_barrier
	s_waitcnt lgkmcnt(0)
	s_waitcnt lgkmcnt(0)
	v_mfma_f32_16x16x32_bf16 v[114:117], v[214:217], v[172:175], v[114:117]
	v_mfma_f32_16x16x32_bf16 v[106:109], v[222:225], v[172:175], v[106:109]
	v_mfma_f32_16x16x32_bf16 v[98:101], v[214:217], v[180:183], v[98:101]
	v_mfma_f32_16x16x32_bf16 v[90:93], v[222:225], v[180:183], v[90:93]
	v_mfma_f32_16x16x32_bf16 v[82:85], v[214:217], v[198:201], v[82:85]
	v_mfma_f32_16x16x32_bf16 v[74:77], v[222:225], v[198:201], v[74:77]
	v_mfma_f32_16x16x32_bf16 v[70:73], v[214:217], v[206:209], v[70:73]
	v_mfma_f32_16x16x32_bf16 v[66:69], v[222:225], v[206:209], v[66:69]
	v_mfma_f32_16x16x32_bf16 v[114:117], v[218:221], v[176:179], v[114:117]
	v_mfma_f32_16x16x32_bf16 v[106:109], v[226:229], v[176:179], v[106:109]
	v_mfma_f32_16x16x32_bf16 v[98:101], v[218:221], v[184:187], v[98:101]
	v_mfma_f32_16x16x32_bf16 v[90:93], v[226:229], v[184:187], v[90:93]
	v_mfma_f32_16x16x32_bf16 v[82:85], v[218:221], v[202:205], v[82:85]
	v_mfma_f32_16x16x32_bf16 v[74:77], v[226:229], v[202:205], v[74:77]
	v_mfma_f32_16x16x32_bf16 v[70:73], v[218:221], v[210:213], v[70:73]
	v_mfma_f32_16x16x32_bf16 v[66:69], v[226:229], v[210:213], v[66:69]
	s_mov_b32 m0, s1
	v_lshl_add_u64 v[232:233], s[24:25], 0, v[130:131]
	s_barrier
	ds_read_b128 v[172:175], v155 offset:16384
	ds_read_b128 v[176:179], v155 offset:17408
	ds_read_b128 v[180:183], v155 offset:18432
	ds_read_b128 v[184:187], v155 offset:19456
	ds_read_b128 v[198:201], v155 offset:20480
	ds_read_b128 v[202:205], v155 offset:21504
	ds_read_b128 v[206:209], v155 offset:22528
	ds_read_b128 v[210:213], v155 offset:23552
	global_load_lds_dwordx4 v[232:233], off
	v_lshl_add_u64 v[234:235], s[24:25], 0, v[134:135]
	s_mov_b32 m0, s27
	s_nop 0
	global_load_lds_dwordx4 v[234:235], off
	s_barrier
	s_waitcnt lgkmcnt(0)
	s_waitcnt lgkmcnt(0)
	v_mfma_f32_16x16x32_bf16 v[62:65], v[156:159], v[172:175], v[62:65]
	v_mfma_f32_16x16x32_bf16 v[58:61], v[164:167], v[172:175], v[58:61]
	v_mfma_f32_16x16x32_bf16 v[54:57], v[156:159], v[180:183], v[54:57]
	v_mfma_f32_16x16x32_bf16 v[46:49], v[164:167], v[180:183], v[46:49]
	v_mfma_f32_16x16x32_bf16 v[38:41], v[156:159], v[198:201], v[38:41]
	v_mfma_f32_16x16x32_bf16 v[30:33], v[164:167], v[198:201], v[30:33]
	v_mfma_f32_16x16x32_bf16 v[22:25], v[156:159], v[206:209], v[22:25]
	v_mfma_f32_16x16x32_bf16 v[14:17], v[164:167], v[206:209], v[14:17]
	v_mfma_f32_16x16x32_bf16 v[62:65], v[160:163], v[176:179], v[62:65]
	v_mfma_f32_16x16x32_bf16 v[58:61], v[168:171], v[176:179], v[58:61]
	v_mfma_f32_16x16x32_bf16 v[54:57], v[160:163], v[184:187], v[54:57]
	v_mfma_f32_16x16x32_bf16 v[46:49], v[168:171], v[184:187], v[46:49]
	v_mfma_f32_16x16x32_bf16 v[38:41], v[160:163], v[202:205], v[38:41]
	v_mfma_f32_16x16x32_bf16 v[30:33], v[168:171], v[202:205], v[30:33]
	v_mfma_f32_16x16x32_bf16 v[22:25], v[160:163], v[210:213], v[22:25]
	v_mfma_f32_16x16x32_bf16 v[14:17], v[168:171], v[210:213], v[14:17]
	s_barrier
; #define PG8_STAGE(bufoff, gbase, voff) do { _Pragma("unroll") for (int _i = 0; _i < 2; ++_i) \
;         __builtin_amdgcn_global_load_lds((const unsigned*)((const char*)(gbase) + (voff)[_i]), (LAS unsigned*)(lds + (bufoff) + ldsw + _i * 8192), 16, 0, 0); } while (0)
; #define PG8_LDA(dst, b, h) do { _Pragma("unroll") for (int m = 0; m < 4; ++m) _Pragma("unroll") for (int k = 0; k < 2; ++k) dst[m][k] = *(const LAS bf16x8*)(lds + PG8_SA(b, h) + aoff + m * 2048 + k * 1024); } while (0)
; #define PG8_LDB(dst, b, h) do { _Pragma("unroll") for (int n = 0; n < 2; ++n) _Pragma("unroll") for (int k = 0; k < 2; ++k) dst[n][k] = *(const LAS bf16x8*)(lds + PG8_SB(b, h) + boff + n * 2048 + k * 1024); } while (0)
; #define PG8_MMA(ai, bj, At, Bt) do { __builtin_amdgcn_s_setprio(1); _Pragma("unroll") for (int m = 0; m < 4; ++m) _Pragma("unroll") for (int n = 0; n < 2; ++n) _Pragma("unroll") for (int k = 0; k < 2; ++k) \
;         acc[ai][bj][m][n] = __builtin_amdgcn_mfma_f32_16x16x32_bf16(Bt[n][k], At[m][k], acc[ai][bj][m][n], 0, 0, 0); __builtin_amdgcn_s_setprio(0); } while (0)
; #define PG8_WAIT_V(n) asm volatile("s_waitcnt vmcnt(" #n ")" ::: "memory")
; #define PG8_WAIT_L(n) asm volatile("s_waitcnt lgkmcnt(" #n ")" ::: "memory")
; #define PG8_BAR __builtin_amdgcn_s_barrier()
; #define PG8_SCHED __builtin_amdgcn_sched_barrier(0)
; template <class Epi>
; DEV void gemm_phase(LAS unsigned char* lds, const int tid, const Gemm g, const StaticOrder& S, const Epi& E) {
;     ...
;             PG8_BAR; PG8_WAIT_L(0); PG8_MMA(1, 0, At, B0); PG8_BAR; PG8_SCHED;
;             PG8_STAGE(PG8_SB(0, 1), b2 + hstep, voffB);
;             PG8_WAIT_V(6); PG8_BAR; PG8_MMA(1, 1, At, B1); PG8_BAR;
;             PG8_LDB(B0, 1, 0); PG8_SCHED; PG8_LDA(At, 1, 0); PG8_STAGE(PG8_SA(0, 1), a2 + hstep, voffA);
;             PG8_WAIT_L(8); PG8_BAR; PG8_WAIT_L(0); PG8_MMA(0, 0, At, B0); PG8_BAR; PG8_SCHED;
;             PG8_LDB(B1, 1, 1); PG8_STAGE(PG8_SB(1, 0), b3, voffB);
;             PG8_BAR; PG8_WAIT_L(0); PG8_MMA(0, 1, At, B1); PG8_BAR;
;             PG8_LDA(At, 1, 1); PG8_STAGE(PG8_SA(1, 0), a3, voffA);
;             PG8_BAR; PG8_WAIT_L(0); PG8_MMA(1, 0, At, B0); PG8_BAR; PG8_SCHED;
	s_add_u32 s40, s6, 0x40000
	s_addc_u32 s41, s7, 0
	s_add_i32 s42, s42, s26
	v_lshl_add_u64 v[156:157], s[40:41], 0, v[132:133]
	s_mov_b32 m0, s42
	s_nop 0
	global_load_lds_dwordx4 v[156:157], off
	v_lshl_add_u64 v[156:157], s[40:41], 0, v[136:137]
	s_add_i32 m0, s42, 0x2000
	s_nop 0
	global_load_lds_dwordx4 v[156:157], off
	s_waitcnt vmcnt(6)
	s_barrier
	v_mfma_f32_16x16x32_bf16 v[50:53], v[214:217], v[172:175], v[50:53]
	v_mfma_f32_16x16x32_bf16 v[42:45], v[222:225], v[172:175], v[42:45]
	v_mfma_f32_16x16x32_bf16 v[34:37], v[214:217], v[180:183], v[34:37]
	v_mfma_f32_16x16x32_bf16 v[26:29], v[222:225], v[180:183], v[26:29]
	v_mfma_f32_16x16x32_bf16 v[18:21], v[214:217], v[198:201], v[18:21]
	v_mfma_f32_16x16x32_bf16 v[10:13], v[222:225], v[198:201], v[10:13]
	v_mfma_f32_16x16x32_bf16 v[6:9], v[214:217], v[206:209], v[6:9]
	v_mfma_f32_16x16x32_bf16 v[2:5], v[222:225], v[206:209], v[2:5]
	v_mfma_f32_16x16x32_bf16 v[50:53], v[218:221], v[176:179], v[50:53]
	v_mfma_f32_16x16x32_bf16 v[42:45], v[226:229], v[176:179], v[42:45]
	v_mfma_f32_16x16x32_bf16 v[34:37], v[218:221], v[184:187], v[34:37]
	v_mfma_f32_16x16x32_bf16 v[26:29], v[226:229], v[184:187], v[26:29]
	v_mfma_f32_16x16x32_bf16 v[18:21], v[218:221], v[202:205], v[18:21]
	v_mfma_f32_16x16x32_bf16 v[10:13], v[226:229], v[202:205], v[10:13]
	v_mfma_f32_16x16x32_bf16 v[6:9], v[218:221], v[210:213], v[6:9]
	v_mfma_f32_16x16x32_bf16 v[2:5], v[226:229], v[210:213], v[2:5]
	s_add_i32 s40, 0, 0x18000
	v_add_u32_e32 v168, s40, v1
	s_barrier
	ds_read_b128 v[156:159], v168
	ds_read_b128 v[160:163], v168 offset:1024
	ds_read_b128 v[164:167], v168 offset:2048
	ds_read_b128 v[168:171], v168 offset:3072
	s_add_u32 s24, s24, 0x40000
	s_addc_u32 s25, s25, 0
	s_mov_b32 m0, s28
	v_lshl_add_u64 v[214:215], s[24:25], 0, v[130:131]
	ds_read_b128 v[172:175], v155 offset:32768
	ds_read_b128 v[176:179], v155 offset:33792
	ds_read_b128 v[180:183], v155 offset:34816
	ds_read_b128 v[184:187], v155 offset:35840
	ds_read_b128 v[198:201], v155 offset:36864
	ds_read_b128 v[202:205], v155 offset:37888
	ds_read_b128 v[206:209], v155 offset:38912
	ds_read_b128 v[210:213], v155 offset:39936
	global_load_lds_dwordx4 v[214:215], off
	v_lshl_add_u64 v[214:215], s[24:25], 0, v[134:135]
	s_mov_b32 m0, s29
	s_nop 0
	global_load_lds_dwordx4 v[214:215], off
	s_waitcnt lgkmcnt(8)
	s_barrier
	s_waitcnt lgkmcnt(0)
	s_waitcnt lgkmcnt(0)
	v_mfma_f32_16x16x32_bf16 v[126:129], v[156:159], v[172:175], v[126:129]
	v_mfma_f32_16x16x32_bf16 v[122:125], v[164:167], v[172:175], v[122:125]
	v_mfma_f32_16x16x32_bf16 v[118:121], v[156:159], v[180:183], v[118:121]
	v_mfma_f32_16x16x32_bf16 v[110:113], v[164:167], v[180:183], v[110:113]
	v_mfma_f32_16x16x32_bf16 v[102:105], v[156:159], v[198:201], v[102:105]
	v_mfma_f32_16x16x32_bf16 v[94:97], v[164:167], v[198:201], v[94:97]
	v_mfma_f32_16x16x32_bf16 v[86:89], v[156:159], v[206:209], v[86:89]
	v_mfma_f32_16x16x32_bf16 v[78:81], v[164:167], v[206:209], v[78:81]
	v_mfma_f32_16x16x32_bf16 v[126:129], v[160:163], v[176:179], v[126:129]
	v_mfma_f32_16x16x32_bf16 v[122:125], v[168:171], v[176:179], v[122:125]
	v_mfma_f32_16x16x32_bf16 v[118:121], v[160:163], v[184:187], v[118:121]
	v_mfma_f32_16x16x32_bf16 v[110:113], v[168:171], v[184:187], v[110:113]
	v_mfma_f32_16x16x32_bf16 v[102:105], v[160:163], v[202:205], v[102:105]
	v_mfma_f32_16x16x32_bf16 v[94:97], v[168:171], v[202:205], v[94:97]
	v_mfma_f32_16x16x32_bf16 v[86:89], v[160:163], v[210:213], v[86:89]
	v_mfma_f32_16x16x32_bf16 v[78:81], v[168:171], v[210:213], v[78:81]
	s_barrier
	s_add_i32 s24, 0, 0x1c000
	s_add_i32 s25, s40, s26
	v_add_u32_e32 v226, s24, v1
	v_lshl_add_u64 v[152:153], v[152:153], 0, s[10:11]
	s_mov_b32 m0, s25
	ds_read_b128 v[214:217], v226
	ds_read_b128 v[218:221], v226 offset:1024
	ds_read_b128 v[222:225], v226 offset:2048
	ds_read_b128 v[226:229], v226 offset:3072
	global_load_lds_dwordx4 v[152:153], off
	v_lshl_add_u64 v[152:153], v[230:231], 0, s[10:11]
	s_add_i32 m0, s25, 0x2000
	s_nop 0
	global_load_lds_dwordx4 v[152:153], off
	s_barrier
	s_waitcnt lgkmcnt(0)
	s_waitcnt lgkmcnt(0)
	v_mfma_f32_16x16x32_bf16 v[114:117], v[214:217], v[172:175], v[114:117]
	v_mfma_f32_16x16x32_bf16 v[106:109], v[222:225], v[172:175], v[106:109]
	v_mfma_f32_16x16x32_bf16 v[98:101], v[214:217], v[180:183], v[98:101]
	v_mfma_f32_16x16x32_bf16 v[90:93], v[222:225], v[180:183], v[90:93]
	v_mfma_f32_16x16x32_bf16 v[82:85], v[214:217], v[198:201], v[82:85]
	v_mfma_f32_16x16x32_bf16 v[74:77], v[222:225], v[198:201], v[74:77]
	v_mfma_f32_16x16x32_bf16 v[70:73], v[214:217], v[206:209], v[70:73]
	v_mfma_f32_16x16x32_bf16 v[66:69], v[222:225], v[206:209], v[66:69]
	v_mfma_f32_16x16x32_bf16 v[114:117], v[218:221], v[176:179], v[114:117]
	v_mfma_f32_16x16x32_bf16 v[106:109], v[226:229], v[176:179], v[106:109]
	v_mfma_f32_16x16x32_bf16 v[98:101], v[218:221], v[184:187], v[98:101]
	v_mfma_f32_16x16x32_bf16 v[90:93], v[226:229], v[184:187], v[90:93]
	v_mfma_f32_16x16x32_bf16 v[82:85], v[218:221], v[202:205], v[82:85]
	v_mfma_f32_16x16x32_bf16 v[74:77], v[226:229], v[202:205], v[74:77]
	v_mfma_f32_16x16x32_bf16 v[70:73], v[218:221], v[210:213], v[70:73]
	v_mfma_f32_16x16x32_bf16 v[66:69], v[226:229], v[210:213], v[66:69]
	s_mov_b32 m0, s30
	v_lshl_add_u64 v[152:153], v[232:233], 0, s[10:11]
	s_barrier
	ds_read_b128 v[172:175], v155 offset:49152
	ds_read_b128 v[176:179], v155 offset:50176
	ds_read_b128 v[180:183], v155 offset:51200
	ds_read_b128 v[184:187], v155 offset:52224
	ds_read_b128 v[198:201], v155 offset:53248
	ds_read_b128 v[202:205], v155 offset:54272
	ds_read_b128 v[206:209], v155 offset:55296
	ds_read_b128 v[210:213], v155 offset:56320
	global_load_lds_dwordx4 v[152:153], off
	v_lshl_add_u64 v[152:153], v[234:235], 0, s[10:11]
	s_mov_b32 m0, s31
	s_nop 0
	global_load_lds_dwordx4 v[152:153], off
	s_barrier
; #define PG8_STAGE(bufoff, gbase, voff) do { _Pragma("unroll") for (int _i = 0; _i < 2; ++_i) \
;         __builtin_amdgcn_global_load_lds((const unsigned*)((const char*)(gbase) + (voff)[_i]), (LAS unsigned*)(lds + (bufoff) + ldsw + _i * 8192), 16, 0, 0); } while (0)
; #define PG8_MMA(ai, bj, At, Bt) do { __builtin_amdgcn_s_setprio(1); _Pragma("unroll") for (int m = 0; m < 4; ++m) _Pragma("unroll") for (int n = 0; n < 2; ++n) _Pragma("unroll") for (int k = 0; k < 2; ++k) \
;         acc[ai][bj][m][n] = __builtin_amdgcn_mfma_f32_16x16x32_bf16(Bt[n][k], At[m][k], acc[ai][bj][m][n], 0, 0, 0); __builtin_amdgcn_s_setprio(0); } while (0)
; #define PG8_WAIT_V(n) asm volatile("s_waitcnt vmcnt(" #n ")" ::: "memory")
; #define PG8_WAIT_L(n) asm volatile("s_waitcnt lgkmcnt(" #n ")" ::: "memory")
; #define PG8_BAR __builtin_amdgcn_s_barrier()
; #define PG8_SCHED __builtin_amdgcn_sched_barrier(0)
; template <class Epi>
; DEV void gemm_phase(LAS unsigned char* lds, const int tid, const Gemm g, const StaticOrder& S, const Epi& E) {
;     ...
;             PG8_BAR; PG8_WAIT_L(0); PG8_MMA(1, 0, At, B0); PG8_BAR; PG8_SCHED;
;             PG8_STAGE(PG8_SB(1, 1), b3 + hstep, voffB);
;             PG8_WAIT_V(6); PG8_BAR; PG8_MMA(1, 1, At, B1); PG8_BAR;
;         }
	s_waitcnt lgkmcnt(0)
	s_waitcnt lgkmcnt(0)
	v_mfma_f32_16x16x32_bf16 v[62:65], v[156:159], v[172:175], v[62:65]
	v_mfma_f32_16x16x32_bf16 v[58:61], v[164:167], v[172:175], v[58:61]
	v_mfma_f32_16x16x32_bf16 v[54:57], v[156:159], v[180:183], v[54:57]
	v_mfma_f32_16x16x32_bf16 v[46:49], v[164:167], v[180:183], v[46:49]
	v_mfma_f32_16x16x32_bf16 v[38:41], v[156:159], v[198:201], v[38:41]
	v_mfma_f32_16x16x32_bf16 v[30:33], v[164:167], v[198:201], v[30:33]
	v_mfma_f32_16x16x32_bf16 v[22:25], v[156:159], v[206:209], v[22:25]
	v_mfma_f32_16x16x32_bf16 v[14:17], v[164:167], v[206:209], v[14:17]
	v_mfma_f32_16x16x32_bf16 v[62:65], v[160:163], v[176:179], v[62:65]
	v_mfma_f32_16x16x32_bf16 v[58:61], v[168:171], v[176:179], v[58:61]
	v_mfma_f32_16x16x32_bf16 v[54:57], v[160:163], v[184:187], v[54:57]
	v_mfma_f32_16x16x32_bf16 v[46:49], v[168:171], v[184:187], v[46:49]
	v_mfma_f32_16x16x32_bf16 v[38:41], v[160:163], v[202:205], v[38:41]
	v_mfma_f32_16x16x32_bf16 v[30:33], v[168:171], v[202:205], v[30:33]
	v_mfma_f32_16x16x32_bf16 v[22:25], v[160:163], v[210:213], v[22:25]
	v_mfma_f32_16x16x32_bf16 v[14:17], v[168:171], v[210:213], v[14:17]
	s_barrier
	s_add_u32 s6, s6, 0x40080
	s_addc_u32 s7, s7, 0
	s_add_i32 s24, s24, s26
	v_lshl_add_u64 v[152:153], s[6:7], 0, v[132:133]
	s_mov_b32 m0, s24
	s_nop 0
	global_load_lds_dwordx4 v[152:153], off
	v_lshl_add_u64 v[152:153], s[6:7], 0, v[136:137]
	s_add_i32 m0, s24, 0x2000
	s_nop 0
	global_load_lds_dwordx4 v[152:153], off
	s_waitcnt vmcnt(6)
	s_barrier
	v_mfma_f32_16x16x32_bf16 v[50:53], v[214:217], v[172:175], v[50:53]
	v_mfma_f32_16x16x32_bf16 v[42:45], v[222:225], v[172:175], v[42:45]
	v_mfma_f32_16x16x32_bf16 v[34:37], v[214:217], v[180:183], v[34:37]
	v_mfma_f32_16x16x32_bf16 v[26:29], v[222:225], v[180:183], v[26:29]
	v_mfma_f32_16x16x32_bf16 v[18:21], v[214:217], v[198:201], v[18:21]
	v_mfma_f32_16x16x32_bf16 v[10:13], v[222:225], v[198:201], v[10:13]
	v_mfma_f32_16x16x32_bf16 v[6:9], v[214:217], v[206:209], v[6:9]
	v_mfma_f32_16x16x32_bf16 v[2:5], v[222:225], v[206:209], v[2:5]
	v_mfma_f32_16x16x32_bf16 v[50:53], v[218:221], v[176:179], v[50:53]
	v_mfma_f32_16x16x32_bf16 v[42:45], v[226:229], v[176:179], v[42:45]
	v_mfma_f32_16x16x32_bf16 v[34:37], v[218:221], v[184:187], v[34:37]
	v_mfma_f32_16x16x32_bf16 v[26:29], v[226:229], v[184:187], v[26:29]
	v_mfma_f32_16x16x32_bf16 v[18:21], v[218:221], v[202:205], v[18:21]
	v_mfma_f32_16x16x32_bf16 v[10:13], v[226:229], v[202:205], v[10:13]
	v_mfma_f32_16x16x32_bf16 v[6:9], v[218:221], v[210:213], v[6:9]
	v_mfma_f32_16x16x32_bf16 v[2:5], v[226:229], v[210:213], v[2:5]
	s_setprio 0
	s_add_i32 s39, s39, 2
	s_add_u32 s22, s22, 0x100
	s_addc_u32 s23, s23, 0
	s_add_u32 s37, s37, 0x100
	s_addc_u32 s38, s38, 0
	s_cmp_gt_u32 s39, 13
	s_barrier
	s_cbranch_scc0 .LBB0_1003
; DEV unsigned cvt_pk_bf16(float lo, float hi) { unsigned r; asm volatile("v_cvt_pk_bf16_f32 %0, %1, %2" : "=v"(r) : "v"(lo), "v"(hi)); return r; }
; #define PG8_WAIT_V(n) asm volatile("s_waitcnt vmcnt(" #n ")" ::: "memory")
; #define PG8_BAR __builtin_amdgcn_s_barrier()
;     DEV void operator()(const f32x4 (&acc)[2][2][4][2], const Unit& u, int wr, int wc, int fr, int fq) const {
;         const int row0 = prow(u.pm) + wr * 64 + fr; const int col0 = u.pn * BM + wc * 32 + 8 * fq;
; #pragma unroll
;         for (int ai = 0; ai < 2; ++ai)
; #pragma unroll
;             for (int m = 0; m < 4; ++m) { bf16_t* rowp = O + (size_t)(row0 + ai * HALF + m * 16) * ldc + col0;
; #pragma unroll
;                 for (int bj = 0; bj < 2; ++bj) { const f32x4 v0 = acc[ai][bj][m][0], v1 = acc[ai][bj][m][1];
;                     u32x4 w; w.x = cvt_pk_bf16(v0[0], v0[1]); w.y = cvt_pk_bf16(v0[2], v0[3]); w.z = cvt_pk_bf16(v1[0], v1[1]); w.w = cvt_pk_bf16(v1[2], v1[3]);
;                     *(u32x4*)(rowp + bj * HALF) = w; } }
;     }
; template <class Epi>
; DEV void gemm_phase(LAS unsigned char* lds, const int tid, const Gemm g, const StaticOrder& S, const Epi& E) {
;     ...
;         E(acc, cur, wr, wc, fr, fq);
;         if (!has_next) break;
; #pragma unroll
;         for (int a = 0; a < 2; ++a)
; #pragma unroll
;             for (int b = 0; b < 2; ++b)
; #pragma unroll
;                 for (int m = 0; m < 4; ++m)
; #pragma unroll
;                     for (int n = 0; n < 2; ++n) acc[a][b][m][n] = (f32x4){0.f, 0.f, 0.f, 0.f};
;         cur = nxt; cA = nA; cB = nB; ++ui;
;     }
;     PG8_WAIT_V(0);
;     if (wr == 0) PG8_BAR;
;     PG8_BAR;
	s_lshl_b32 s6, s34, 2
	s_lshl_b32 s3, s34, 8
	s_and_b32 s6, s6, 0xffffff00
	s_add_i32 s6, s6, s3
	v_add_u32_e32 v156, s6, v141
	v_lshl_or_b32 v152, s0, 8, v154
	v_ashrrev_i32_e32 v157, 31, v156
	v_ashrrev_i32_e32 v153, 31, v152
	v_lshlrev_b64 v[158:159], 11, v[156:157]
	v_lshl_add_u64 v[158:159], s[78:79], 0, v[158:159]
	v_lshlrev_b64 v[160:161], 1, v[152:153]
	v_lshl_add_u64 v[152:153], v[158:159], 0, v[160:161]
	v_cvt_pk_bf16_f32 v126, v126, v127
	v_cvt_pk_bf16_f32 v127, v128, v129
	v_cvt_pk_bf16_f32 v128, v122, v123
	v_cvt_pk_bf16_f32 v129, v124, v125
	global_store_dwordx4 v[152:153], v[126:129], off
	v_cvt_pk_bf16_f32 v114, v114, v115
	v_cvt_pk_bf16_f32 v115, v116, v117
	v_cvt_pk_bf16_f32 v116, v106, v107
	v_or_b32_e32 v106, 16, v156
	v_ashrrev_i32_e32 v107, 31, v106
	v_lshlrev_b64 v[106:107], 11, v[106:107]
	v_lshl_add_u64 v[106:107], s[78:79], 0, v[106:107]
	v_cvt_pk_bf16_f32 v117, v108, v109
	global_store_dwordx4 v[152:153], v[114:117], off offset:256
	s_mov_b32 s0, 0x40000
	s_mov_b64 s[6:7], 0x40000
	v_lshl_add_u64 v[114:115], v[106:107], 0, v[160:161]
	v_cvt_pk_bf16_f32 v106, v118, v119
	v_cvt_pk_bf16_f32 v107, v120, v121
	v_cvt_pk_bf16_f32 v108, v110, v111
	v_cvt_pk_bf16_f32 v109, v112, v113
	global_store_dwordx4 v[114:115], v[106:109], off
	v_cvt_pk_bf16_f32 v98, v98, v99
	v_cvt_pk_bf16_f32 v99, v100, v101
	v_cvt_pk_bf16_f32 v100, v90, v91
	v_or_b32_e32 v90, 32, v156
	v_ashrrev_i32_e32 v91, 31, v90
	v_lshlrev_b64 v[90:91], 11, v[90:91]
	v_lshl_add_u64 v[90:91], s[78:79], 0, v[90:91]
	v_cvt_pk_bf16_f32 v101, v92, v93
	global_store_dwordx4 v[114:115], v[98:101], off offset:256
	s_mov_b32 s34, s35
	s_mov_b32 s36, s2
	v_lshl_add_u64 v[98:99], v[90:91], 0, v[160:161]
	v_cvt_pk_bf16_f32 v90, v102, v103
	v_cvt_pk_bf16_f32 v91, v104, v105
	v_cvt_pk_bf16_f32 v92, v94, v95
	v_cvt_pk_bf16_f32 v93, v96, v97
	global_store_dwordx4 v[98:99], v[90:93], off
	v_cvt_pk_bf16_f32 v82, v82, v83
	v_cvt_pk_bf16_f32 v83, v84, v85
	v_cvt_pk_bf16_f32 v84, v74, v75
	v_or_b32_e32 v74, 48, v156
	v_ashrrev_i32_e32 v75, 31, v74
	v_lshlrev_b64 v[74:75], 11, v[74:75]
	v_lshl_add_u64 v[74:75], s[78:79], 0, v[74:75]
	v_cvt_pk_bf16_f32 v85, v76, v77
	global_store_dwordx4 v[98:99], v[82:85], off offset:256
	s_mov_b32 s37, s35
	s_mov_b64 s[24:25], s[20:21]
	v_lshl_add_u64 v[82:83], v[74:75], 0, v[160:161]
	v_cvt_pk_bf16_f32 v74, v86, v87
	v_cvt_pk_bf16_f32 v75, v88, v89
	v_cvt_pk_bf16_f32 v76, v78, v79
	v_cvt_pk_bf16_f32 v77, v80, v81
	global_store_dwordx4 v[82:83], v[74:77], off
	v_cvt_pk_bf16_f32 v70, v70, v71
	v_cvt_pk_bf16_f32 v71, v72, v73
	v_cvt_pk_bf16_f32 v72, v66, v67
	v_cvt_pk_bf16_f32 v73, v68, v69
	global_store_dwordx4 v[82:83], v[70:73], off offset:256
	v_cvt_pk_bf16_f32 v62, v62, v63
	v_cvt_pk_bf16_f32 v63, v64, v65
	v_cvt_pk_bf16_f32 v64, v58, v59
	v_add_co_u32_e32 v58, vcc, s0, v152
	v_lshl_add_u64 v[66:67], v[152:153], 0, s[6:7]
	s_nop 0
	v_addc_co_u32_e32 v59, vcc, 0, v153, vcc
	s_mov_b32 s0, 0x48000
	v_cvt_pk_bf16_f32 v65, v60, v61
	global_store_dwordx4 v[58:59], v[62:65], off
	v_cvt_pk_bf16_f32 v50, v50, v51
	v_cvt_pk_bf16_f32 v51, v52, v53
	v_cvt_pk_bf16_f32 v52, v42, v43
	v_cvt_pk_bf16_f32 v53, v44, v45
	global_store_dwordx4 v[66:67], v[50:53], off offset:256
	s_mov_b64 s[6:7], 0x48000
	v_cvt_pk_bf16_f32 v42, v54, v55
	v_cvt_pk_bf16_f32 v43, v56, v57
	v_cvt_pk_bf16_f32 v44, v46, v47
	v_add_co_u32_e32 v46, vcc, s0, v152
	v_lshl_add_u64 v[50:51], v[152:153], 0, s[6:7]
	s_nop 0
	v_addc_co_u32_e32 v47, vcc, 0, v153, vcc
	s_mov_b32 s0, 0x50000
	v_cvt_pk_bf16_f32 v45, v48, v49
	global_store_dwordx4 v[46:47], v[42:45], off
	v_cvt_pk_bf16_f32 v34, v34, v35
	v_cvt_pk_bf16_f32 v35, v36, v37
	v_cvt_pk_bf16_f32 v36, v26, v27
	v_cvt_pk_bf16_f32 v37, v28, v29
	global_store_dwordx4 v[50:51], v[34:37], off offset:256
	s_mov_b64 s[6:7], 0x50000
	v_cvt_pk_bf16_f32 v26, v38, v39
	v_cvt_pk_bf16_f32 v27, v40, v41
	v_cvt_pk_bf16_f32 v28, v30, v31
	v_add_co_u32_e32 v30, vcc, s0, v152
	v_lshl_add_u64 v[34:35], v[152:153], 0, s[6:7]
	s_nop 0
	v_addc_co_u32_e32 v31, vcc, 0, v153, vcc
	s_mov_b32 s0, 0x58000
	v_cvt_pk_bf16_f32 v29, v32, v33
	global_store_dwordx4 v[30:31], v[26:29], off
	v_cvt_pk_bf16_f32 v18, v18, v19
	v_cvt_pk_bf16_f32 v19, v20, v21
	v_cvt_pk_bf16_f32 v20, v10, v11
	v_cvt_pk_bf16_f32 v21, v12, v13
	global_store_dwordx4 v[34:35], v[18:21], off offset:256
	v_cvt_pk_bf16_f32 v10, v22, v23
	v_cvt_pk_bf16_f32 v11, v24, v25
	v_cvt_pk_bf16_f32 v12, v14, v15
	v_add_co_u32_e32 v14, vcc, s0, v152
	s_mov_b64 s[6:7], 0x58000
	s_nop 0
	v_addc_co_u32_e32 v15, vcc, 0, v153, vcc
	v_lshl_add_u64 v[18:19], v[152:153], 0, s[6:7]
	s_and_b64 vcc, exec, s[16:17]
	s_mov_b32 s0, s2
	s_mov_b64 s[22:23], s[18:19]
	v_cvt_pk_bf16_f32 v13, v16, v17
	global_store_dwordx4 v[14:15], v[10:13], off
	v_cvt_pk_bf16_f32 v6, v6, v7
	v_cvt_pk_bf16_f32 v7, v8, v9
	v_cvt_pk_bf16_f32 v8, v2, v3
	v_cvt_pk_bf16_f32 v9, v4, v5
	global_store_dwordx4 v[18:19], v[6:9], off offset:256
	s_cbranch_vccz .LBB0_989
	s_waitcnt vmcnt(0)
	s_cmpk_gt_u32 s15, 0xff
	s_cbranch_scc1 .LBB0_1007
	s_barrier

; #define PG8_STAGE(bufoff, gbase, voff) do { _Pragma("unroll") for (int _i = 0; _i < 2; ++_i) \
;         __builtin_amdgcn_global_load_lds((const unsigned*)((const char*)(gbase) + (voff)[_i]), (LAS unsigned*)(lds + (bufoff) + ldsw + _i * 8192), 16, 0, 0); } while (0)
; #define PG8_LDA(dst, b, h) do { _Pragma("unroll") for (int m = 0; m < 4; ++m) _Pragma("unroll") for (int k = 0; k < 2; ++k) dst[m][k] = *(const LAS bf16x8*)(lds + PG8_SA(b, h) + aoff + m * 2048 + k * 1024); } while (0)
; #define PG8_LDB(dst, b, h) do { _Pragma("unroll") for (int n = 0; n < 2; ++n) _Pragma("unroll") for (int k = 0; k < 2; ++k) dst[n][k] = *(const LAS bf16x8*)(lds + PG8_SB(b, h) + boff + n * 2048 + k * 1024); } while (0)
; #define PG8_MMA(ai, bj, At, Bt) do { __builtin_amdgcn_s_setprio(1); _Pragma("unroll") for (int m = 0; m < 4; ++m) _Pragma("unroll") for (int n = 0; n < 2; ++n) _Pragma("unroll") for (int k = 0; k < 2; ++k) \
;         acc[ai][bj][m][n] = __builtin_amdgcn_mfma_f32_16x16x32_bf16(Bt[n][k], At[m][k], acc[ai][bj][m][n], 0, 0, 0); __builtin_amdgcn_s_setprio(0); } while (0)
; #define PG8_WAIT_L(n) asm volatile("s_waitcnt lgkmcnt(" #n ")" ::: "memory")
; #define PG8_BAR __builtin_amdgcn_s_barrier()
; #define PG8_SCHED __builtin_amdgcn_sched_barrier(0)
; template <class Epi>
; DEV void gemm_phase(LAS unsigned char* lds, const int tid, const Gemm g, const StaticOrder& S, const Epi& E) {
;     ...
;         for (int t = 0; t < nt; t += 2) {
;             const bool last = (t == nt - 2);
;             const char* a1 = cA + (size_t)(t + 1) * kstep;
;             const char* a2 = last ? nA : cA + (size_t)(t + 2) * kstep; const char* b2 = last ? nB : cB + (size_t)(t + 2) * kstep;
;             const char* a3 = a2 + kstep; const char* b3 = b2 + kstep;
;             PG8_LDB(B0, 0, 0); PG8_SCHED; PG8_LDA(At, 0, 0); PG8_STAGE(PG8_SA(1, 1), a1 + hstep, voffA);
;             PG8_WAIT_L(8); PG8_BAR; PG8_WAIT_L(0); PG8_MMA(0, 0, At, B0); PG8_BAR; PG8_SCHED;
;             PG8_LDB(B1, 0, 1); PG8_STAGE(PG8_SB(0, 0), b2, voffB);
;             PG8_BAR; PG8_WAIT_L(0); PG8_MMA(0, 1, At, B1); PG8_BAR;
;             PG8_LDA(At, 0, 1); PG8_STAGE(PG8_SA(0, 0), a2, voffA);
;             PG8_BAR; PG8_WAIT_L(0); PG8_MMA(1, 0, At, B0); PG8_BAR; PG8_SCHED;
.Lprio_skip_2:
	s_add_u32 s6, s24, 0xfffc0080
	s_addc_u32 s7, s25, -1
	s_add_i32 s49, 0, 0x10000
	v_add_u32_e32 v152, s49, v1
	ds_read_b128 v[156:159], v152
	ds_read_b128 v[160:163], v152 offset:1024
	ds_read_b128 v[164:167], v152 offset:2048
	ds_read_b128 v[168:171], v152 offset:3072
	s_cmp_eq_u32 s48, 12
	s_cselect_b32 s27, s19, s7
	s_cselect_b32 s26, s18, s6
	s_cselect_b32 s7, s1, s47
	s_cselect_b32 s6, s45, s46
	v_lshl_add_u64 v[152:153], s[24:25], 0, v[138:139]
	s_add_i32 m0, s23, 0xc000
	ds_read_b128 v[172:175], v155
	ds_read_b128 v[176:179], v155 offset:1024
	ds_read_b128 v[180:183], v155 offset:2048
	ds_read_b128 v[184:187], v155 offset:3072
	ds_read_b128 v[198:201], v155 offset:4096
	ds_read_b128 v[202:205], v155 offset:5120
	ds_read_b128 v[206:209], v155 offset:6144
	ds_read_b128 v[210:213], v155 offset:7168
	global_load_lds_dwordx4 v[152:153], off
	v_lshl_add_u64 v[152:153], s[24:25], 0, v[150:151]
	s_add_i32 m0, s23, 0xe000
	s_nop 0
	global_load_lds_dwordx4 v[152:153], off
	s_waitcnt lgkmcnt(8)
	s_barrier
	s_waitcnt lgkmcnt(0)
	s_waitcnt lgkmcnt(0)
	v_mfma_f32_16x16x32_bf16 v[126:129], v[156:159], v[172:175], v[126:129]
	v_mfma_f32_16x16x32_bf16 v[118:121], v[164:167], v[172:175], v[118:121]
	v_mfma_f32_16x16x32_bf16 v[110:113], v[156:159], v[180:183], v[110:113]
	v_mfma_f32_16x16x32_bf16 v[102:105], v[164:167], v[180:183], v[102:105]
	v_mfma_f32_16x16x32_bf16 v[94:97], v[156:159], v[198:201], v[94:97]
	v_mfma_f32_16x16x32_bf16 v[86:89], v[164:167], v[198:201], v[86:89]
	v_mfma_f32_16x16x32_bf16 v[78:81], v[156:159], v[206:209], v[78:81]
	v_mfma_f32_16x16x32_bf16 v[70:73], v[164:167], v[206:209], v[70:73]
	v_mfma_f32_16x16x32_bf16 v[126:129], v[160:163], v[176:179], v[126:129]
	v_mfma_f32_16x16x32_bf16 v[118:121], v[168:171], v[176:179], v[118:121]
	v_mfma_f32_16x16x32_bf16 v[110:113], v[160:163], v[184:187], v[110:113]
	v_mfma_f32_16x16x32_bf16 v[102:105], v[168:171], v[184:187], v[102:105]
	v_mfma_f32_16x16x32_bf16 v[94:97], v[160:163], v[202:205], v[94:97]
	v_mfma_f32_16x16x32_bf16 v[86:89], v[168:171], v[202:205], v[86:89]
	v_mfma_f32_16x16x32_bf16 v[78:81], v[160:163], v[210:213], v[78:81]
	v_mfma_f32_16x16x32_bf16 v[70:73], v[168:171], v[210:213], v[70:73]
	s_barrier
	s_add_i32 s52, 0, 0x14000
	v_add_u32_e32 v152, s52, v1
	s_add_i32 s49, s49, s28
	ds_read_b128 v[214:217], v152
	ds_read_b128 v[218:221], v152 offset:1024
	ds_read_b128 v[222:225], v152 offset:2048
	ds_read_b128 v[226:229], v152 offset:3072
	v_lshl_add_u64 v[152:153], s[6:7], 0, v[132:133]
	s_mov_b32 m0, s49
	v_lshl_add_u64 v[230:231], s[6:7], 0, v[136:137]
	global_load_lds_dwordx4 v[152:153], off
	s_add_i32 m0, s49, 0x2000
	s_nop 0
	global_load_lds_dwordx4 v[230:231], off
	s_barrier
	s_waitcnt lgkmcnt(0)
	s_waitcnt lgkmcnt(0)
	v_mfma_f32_16x16x32_bf16 v[122:125], v[214:217], v[172:175], v[122:125]
	v_mfma_f32_16x16x32_bf16 v[114:117], v[222:225], v[172:175], v[114:117]
	v_mfma_f32_16x16x32_bf16 v[106:109], v[214:217], v[180:183], v[106:109]
	v_mfma_f32_16x16x32_bf16 v[98:101], v[222:225], v[180:183], v[98:101]
	v_mfma_f32_16x16x32_bf16 v[90:93], v[214:217], v[198:201], v[90:93]
	v_mfma_f32_16x16x32_bf16 v[82:85], v[222:225], v[198:201], v[82:85]
	v_mfma_f32_16x16x32_bf16 v[74:77], v[214:217], v[206:209], v[74:77]
	v_mfma_f32_16x16x32_bf16 v[66:69], v[222:225], v[206:209], v[66:69]
	v_mfma_f32_16x16x32_bf16 v[122:125], v[218:221], v[176:179], v[122:125]
	v_mfma_f32_16x16x32_bf16 v[114:117], v[226:229], v[176:179], v[114:117]
	v_mfma_f32_16x16x32_bf16 v[106:109], v[218:221], v[184:187], v[106:109]
	v_mfma_f32_16x16x32_bf16 v[98:101], v[226:229], v[184:187], v[98:101]
	v_mfma_f32_16x16x32_bf16 v[90:93], v[218:221], v[202:205], v[90:93]
	v_mfma_f32_16x16x32_bf16 v[82:85], v[226:229], v[202:205], v[82:85]
	v_mfma_f32_16x16x32_bf16 v[74:77], v[218:221], v[210:213], v[74:77]
	v_mfma_f32_16x16x32_bf16 v[66:69], v[226:229], v[210:213], v[66:69]
	s_mov_b32 m0, s23
	v_lshl_add_u64 v[232:233], s[26:27], 0, v[130:131]
	s_barrier
	ds_read_b128 v[172:175], v155 offset:16384
	ds_read_b128 v[176:179], v155 offset:17408
	ds_read_b128 v[180:183], v155 offset:18432
	ds_read_b128 v[184:187], v155 offset:19456
	ds_read_b128 v[198:201], v155 offset:20480
	ds_read_b128 v[202:205], v155 offset:21504
	ds_read_b128 v[206:209], v155 offset:22528
	ds_read_b128 v[210:213], v155 offset:23552
	global_load_lds_dwordx4 v[232:233], off
	v_lshl_add_u64 v[234:235], s[26:27], 0, v[134:135]
	s_mov_b32 m0, s29
	s_nop 0
	global_load_lds_dwordx4 v[234:235], off
	s_barrier
	s_waitcnt lgkmcnt(0)
	s_waitcnt lgkmcnt(0)
	v_mfma_f32_16x16x32_bf16 v[62:65], v[156:159], v[172:175], v[62:65]
	v_mfma_f32_16x16x32_bf16 v[54:57], v[164:167], v[172:175], v[54:57]
	v_mfma_f32_16x16x32_bf16 v[46:49], v[156:159], v[180:183], v[46:49]
	v_mfma_f32_16x16x32_bf16 v[38:41], v[164:167], v[180:183], v[38:41]
	v_mfma_f32_16x16x32_bf16 v[30:33], v[156:159], v[198:201], v[30:33]
	v_mfma_f32_16x16x32_bf16 v[22:25], v[164:167], v[198:201], v[22:25]
	v_mfma_f32_16x16x32_bf16 v[14:17], v[156:159], v[206:209], v[14:17]
	v_mfma_f32_16x16x32_bf16 v[6:9], v[164:167], v[206:209], v[6:9]
	v_mfma_f32_16x16x32_bf16 v[62:65], v[160:163], v[176:179], v[62:65]
	v_mfma_f32_16x16x32_bf16 v[54:57], v[168:171], v[176:179], v[54:57]
	v_mfma_f32_16x16x32_bf16 v[46:49], v[160:163], v[184:187], v[46:49]
	v_mfma_f32_16x16x32_bf16 v[38:41], v[168:171], v[184:187], v[38:41]
	v_mfma_f32_16x16x32_bf16 v[30:33], v[160:163], v[202:205], v[30:33]
	v_mfma_f32_16x16x32_bf16 v[22:25], v[168:171], v[202:205], v[22:25]
	v_mfma_f32_16x16x32_bf16 v[14:17], v[160:163], v[210:213], v[14:17]
	v_mfma_f32_16x16x32_bf16 v[6:9], v[168:171], v[210:213], v[6:9]
	s_barrier
; #define PG8_STAGE(bufoff, gbase, voff) do { _Pragma("unroll") for (int _i = 0; _i < 2; ++_i) \
;         __builtin_amdgcn_global_load_lds((const unsigned*)((const char*)(gbase) + (voff)[_i]), (LAS unsigned*)(lds + (bufoff) + ldsw + _i * 8192), 16, 0, 0); } while (0)
; #define PG8_LDA(dst, b, h) do { _Pragma("unroll") for (int m = 0; m < 4; ++m) _Pragma("unroll") for (int k = 0; k < 2; ++k) dst[m][k] = *(const LAS bf16x8*)(lds + PG8_SA(b, h) + aoff + m * 2048 + k * 1024); } while (0)
; #define PG8_LDB(dst, b, h) do { _Pragma("unroll") for (int n = 0; n < 2; ++n) _Pragma("unroll") for (int k = 0; k < 2; ++k) dst[n][k] = *(const LAS bf16x8*)(lds + PG8_SB(b, h) + boff + n * 2048 + k * 1024); } while (0)
; #define PG8_MMA(ai, bj, At, Bt) do { __builtin_amdgcn_s_setprio(1); _Pragma("unroll") for (int m = 0; m < 4; ++m) _Pragma("unroll") for (int n = 0; n < 2; ++n) _Pragma("unroll") for (int k = 0; k < 2; ++k) \
;         acc[ai][bj][m][n] = __builtin_amdgcn_mfma_f32_16x16x32_bf16(Bt[n][k], At[m][k], acc[ai][bj][m][n], 0, 0, 0); __builtin_amdgcn_s_setprio(0); } while (0)
; #define PG8_WAIT_V(n) asm volatile("s_waitcnt vmcnt(" #n ")" ::: "memory")
; #define PG8_WAIT_L(n) asm volatile("s_waitcnt lgkmcnt(" #n ")" ::: "memory")
; #define PG8_BAR __builtin_amdgcn_s_barrier()
; #define PG8_SCHED __builtin_amdgcn_sched_barrier(0)
; template <class Epi>
; DEV void gemm_phase(LAS unsigned char* lds, const int tid, const Gemm g, const StaticOrder& S, const Epi& E) {
;     ...
;             PG8_BAR; PG8_WAIT_L(0); PG8_MMA(1, 0, At, B0); PG8_BAR; PG8_SCHED;
;             PG8_STAGE(PG8_SB(0, 1), b2 + hstep, voffB);
;             PG8_WAIT_V(6); PG8_BAR; PG8_MMA(1, 1, At, B1); PG8_BAR;
;             PG8_LDB(B0, 1, 0); PG8_SCHED; PG8_LDA(At, 1, 0); PG8_STAGE(PG8_SA(0, 1), a2 + hstep, voffA);
;             PG8_WAIT_L(8); PG8_BAR; PG8_WAIT_L(0); PG8_MMA(0, 0, At, B0); PG8_BAR; PG8_SCHED;
;             PG8_LDB(B1, 1, 1); PG8_STAGE(PG8_SB(1, 0), b3, voffB);
;             PG8_BAR; PG8_WAIT_L(0); PG8_MMA(0, 1, At, B1); PG8_BAR;
;             PG8_LDA(At, 1, 1); PG8_STAGE(PG8_SA(1, 0), a3, voffA);
;             PG8_BAR; PG8_WAIT_L(0); PG8_MMA(1, 0, At, B0); PG8_BAR; PG8_SCHED;
	s_add_u32 s50, s6, 0x40000
	s_addc_u32 s51, s7, 0
	s_add_i32 s49, s52, s28
	v_lshl_add_u64 v[156:157], s[50:51], 0, v[132:133]
	s_mov_b32 m0, s49
	s_nop 0
	global_load_lds_dwordx4 v[156:157], off
	v_lshl_add_u64 v[156:157], s[50:51], 0, v[136:137]
	s_add_i32 m0, s49, 0x2000
	s_nop 0
	global_load_lds_dwordx4 v[156:157], off
	s_waitcnt vmcnt(6)
	s_barrier
	v_mfma_f32_16x16x32_bf16 v[58:61], v[214:217], v[172:175], v[58:61]
	v_mfma_f32_16x16x32_bf16 v[50:53], v[222:225], v[172:175], v[50:53]
	v_mfma_f32_16x16x32_bf16 v[42:45], v[214:217], v[180:183], v[42:45]
	v_mfma_f32_16x16x32_bf16 v[34:37], v[222:225], v[180:183], v[34:37]
	v_mfma_f32_16x16x32_bf16 v[26:29], v[214:217], v[198:201], v[26:29]
	v_mfma_f32_16x16x32_bf16 v[18:21], v[222:225], v[198:201], v[18:21]
	v_mfma_f32_16x16x32_bf16 v[10:13], v[214:217], v[206:209], v[10:13]
	v_mfma_f32_16x16x32_bf16 v[2:5], v[222:225], v[206:209], v[2:5]
	v_mfma_f32_16x16x32_bf16 v[58:61], v[218:221], v[176:179], v[58:61]
	v_mfma_f32_16x16x32_bf16 v[50:53], v[226:229], v[176:179], v[50:53]
	v_mfma_f32_16x16x32_bf16 v[42:45], v[218:221], v[184:187], v[42:45]
	v_mfma_f32_16x16x32_bf16 v[34:37], v[226:229], v[184:187], v[34:37]
	v_mfma_f32_16x16x32_bf16 v[26:29], v[218:221], v[202:205], v[26:29]
	v_mfma_f32_16x16x32_bf16 v[18:21], v[226:229], v[202:205], v[18:21]
	v_mfma_f32_16x16x32_bf16 v[10:13], v[218:221], v[210:213], v[10:13]
	v_mfma_f32_16x16x32_bf16 v[2:5], v[226:229], v[210:213], v[2:5]
	s_add_i32 s49, 0, 0x18000
	v_add_u32_e32 v168, s49, v1
	s_barrier
	ds_read_b128 v[156:159], v168
	ds_read_b128 v[160:163], v168 offset:1024
	ds_read_b128 v[164:167], v168 offset:2048
	ds_read_b128 v[168:171], v168 offset:3072
	s_add_u32 s26, s26, 0x40000
	s_addc_u32 s27, s27, 0
	s_mov_b32 m0, s33
	v_lshl_add_u64 v[214:215], s[26:27], 0, v[130:131]
	ds_read_b128 v[172:175], v155 offset:32768
	ds_read_b128 v[176:179], v155 offset:33792
	ds_read_b128 v[180:183], v155 offset:34816
	ds_read_b128 v[184:187], v155 offset:35840
	ds_read_b128 v[198:201], v155 offset:36864
	ds_read_b128 v[202:205], v155 offset:37888
	ds_read_b128 v[206:209], v155 offset:38912
	ds_read_b128 v[210:213], v155 offset:39936
	global_load_lds_dwordx4 v[214:215], off
	v_lshl_add_u64 v[214:215], s[26:27], 0, v[134:135]
	s_mov_b32 m0, s37
	s_nop 0
	global_load_lds_dwordx4 v[214:215], off
	s_waitcnt lgkmcnt(8)
	s_barrier
	s_waitcnt lgkmcnt(0)
	s_waitcnt lgkmcnt(0)
	v_mfma_f32_16x16x32_bf16 v[126:129], v[156:159], v[172:175], v[126:129]
	v_mfma_f32_16x16x32_bf16 v[118:121], v[164:167], v[172:175], v[118:121]
	v_mfma_f32_16x16x32_bf16 v[110:113], v[156:159], v[180:183], v[110:113]
	v_mfma_f32_16x16x32_bf16 v[102:105], v[164:167], v[180:183], v[102:105]
	v_mfma_f32_16x16x32_bf16 v[94:97], v[156:159], v[198:201], v[94:97]
	v_mfma_f32_16x16x32_bf16 v[86:89], v[164:167], v[198:201], v[86:89]
	v_mfma_f32_16x16x32_bf16 v[78:81], v[156:159], v[206:209], v[78:81]
	v_mfma_f32_16x16x32_bf16 v[70:73], v[164:167], v[206:209], v[70:73]
	v_mfma_f32_16x16x32_bf16 v[126:129], v[160:163], v[176:179], v[126:129]
	v_mfma_f32_16x16x32_bf16 v[118:121], v[168:171], v[176:179], v[118:121]
	v_mfma_f32_16x16x32_bf16 v[110:113], v[160:163], v[184:187], v[110:113]
	v_mfma_f32_16x16x32_bf16 v[102:105], v[168:171], v[184:187], v[102:105]
	v_mfma_f32_16x16x32_bf16 v[94:97], v[160:163], v[202:205], v[94:97]
	v_mfma_f32_16x16x32_bf16 v[86:89], v[168:171], v[202:205], v[86:89]
	v_mfma_f32_16x16x32_bf16 v[78:81], v[160:163], v[210:213], v[78:81]
	v_mfma_f32_16x16x32_bf16 v[70:73], v[168:171], v[210:213], v[70:73]
	s_barrier
	s_add_i32 s26, 0, 0x1c000
	s_add_i32 s27, s49, s28
	v_add_u32_e32 v226, s26, v1
	v_lshl_add_u64 v[152:153], v[152:153], 0, s[10:11]
	s_mov_b32 m0, s27
	ds_read_b128 v[214:217], v226
	ds_read_b128 v[218:221], v226 offset:1024
	ds_read_b128 v[222:225], v226 offset:2048
	ds_read_b128 v[226:229], v226 offset:3072
	global_load_lds_dwordx4 v[152:153], off
	v_lshl_add_u64 v[152:153], v[230:231], 0, s[10:11]
	s_add_i32 m0, s27, 0x2000
	s_nop 0
	global_load_lds_dwordx4 v[152:153], off
	s_barrier
	s_waitcnt lgkmcnt(0)
	s_waitcnt lgkmcnt(0)
	v_mfma_f32_16x16x32_bf16 v[122:125], v[214:217], v[172:175], v[122:125]
	v_mfma_f32_16x16x32_bf16 v[114:117], v[222:225], v[172:175], v[114:117]
	v_mfma_f32_16x16x32_bf16 v[106:109], v[214:217], v[180:183], v[106:109]
	v_mfma_f32_16x16x32_bf16 v[98:101], v[222:225], v[180:183], v[98:101]
	v_mfma_f32_16x16x32_bf16 v[90:93], v[214:217], v[198:201], v[90:93]
	v_mfma_f32_16x16x32_bf16 v[82:85], v[222:225], v[198:201], v[82:85]
	v_mfma_f32_16x16x32_bf16 v[74:77], v[214:217], v[206:209], v[74:77]
	v_mfma_f32_16x16x32_bf16 v[66:69], v[222:225], v[206:209], v[66:69]
	v_mfma_f32_16x16x32_bf16 v[122:125], v[218:221], v[176:179], v[122:125]
	v_mfma_f32_16x16x32_bf16 v[114:117], v[226:229], v[176:179], v[114:117]
	v_mfma_f32_16x16x32_bf16 v[106:109], v[218:221], v[184:187], v[106:109]
	v_mfma_f32_16x16x32_bf16 v[98:101], v[226:229], v[184:187], v[98:101]
	v_mfma_f32_16x16x32_bf16 v[90:93], v[218:221], v[202:205], v[90:93]
	v_mfma_f32_16x16x32_bf16 v[82:85], v[226:229], v[202:205], v[82:85]
	v_mfma_f32_16x16x32_bf16 v[74:77], v[218:221], v[210:213], v[74:77]
	v_mfma_f32_16x16x32_bf16 v[66:69], v[226:229], v[210:213], v[66:69]
	s_mov_b32 m0, s40
	v_lshl_add_u64 v[152:153], v[232:233], 0, s[10:11]
	s_barrier
	ds_read_b128 v[172:175], v155 offset:49152
	ds_read_b128 v[176:179], v155 offset:50176
	ds_read_b128 v[180:183], v155 offset:51200
	ds_read_b128 v[184:187], v155 offset:52224
	ds_read_b128 v[198:201], v155 offset:53248
	ds_read_b128 v[202:205], v155 offset:54272
	ds_read_b128 v[206:209], v155 offset:55296
	ds_read_b128 v[210:213], v155 offset:56320
	global_load_lds_dwordx4 v[152:153], off
	v_lshl_add_u64 v[152:153], v[234:235], 0, s[10:11]
	s_mov_b32 m0, s41
	s_nop 0
	global_load_lds_dwordx4 v[152:153], off
	s_barrier
; DEV unsigned cvt_pk_bf16(float lo, float hi) { unsigned r; asm volatile("v_cvt_pk_bf16_f32 %0, %1, %2" : "=v"(r) : "v"(lo), "v"(hi)); return r; }
; #define PG8_STAGE(bufoff, gbase, voff) do { _Pragma("unroll") for (int _i = 0; _i < 2; ++_i) \
;         __builtin_amdgcn_global_load_lds((const unsigned*)((const char*)(gbase) + (voff)[_i]), (LAS unsigned*)(lds + (bufoff) + ldsw + _i * 8192), 16, 0, 0); } while (0)
; #define PG8_WAIT_V(n) asm volatile("s_waitcnt vmcnt(" #n ")" ::: "memory")
; #define PG8_BAR __builtin_amdgcn_s_barrier()
;     DEV void operator()(const f32x4 (&acc)[2][2][4][2], const Unit& u, int wr, int wc, int fr, int fq) const {
;         const int row0 = prow(u.pm) + wr * 64 + fr; const int col0 = u.pn * HALF + wc * 32 + 8 * fq;
; #pragma unroll
;         for (int ai = 0; ai < 2; ++ai)
; #pragma unroll
;             for (int m = 0; m < 4; ++m) { bf16_t* rowp = O + (size_t)(row0 + ai * HALF + m * 16) * FH + col0;
;                 typedef float f32x2 __attribute__((ext_vector_type(2)));
;                 f32x2 gv[4], uv[4], ev[4], ov[4];
; #pragma unroll
;                 for (int q = 0; q < 4; ++q) { const int n = q >> 1, j = (q & 1) * 2; gv[q] = (f32x2){acc[ai][0][m][n][j], acc[ai][0][m][n][j + 1]}; uv[q] = (f32x2){acc[ai][1][m][n][j], acc[ai][1][m][n][j + 1]}; }
; #pragma unroll
;                 for (int q = 0; q < 4; ++q) { const f32x2 t = gv[q] * -1.44269504089f; ev[q].x = __builtin_amdgcn_exp2f(t.x); ev[q].y = __builtin_amdgcn_exp2f(t.y); }
; #pragma unroll
;                 for (int q = 0; q < 4; ++q) { const f32x2 d = ev[q] + 1.0f; f32x2 r; r.x = __builtin_amdgcn_rcpf(d.x); r.y = __builtin_amdgcn_rcpf(d.y); ov[q] = (gv[q] * r) * uv[q]; }
;                 float o[8];
; #pragma unroll
;                 for (int q = 0; q < 4; ++q) { o[2 * q] = ov[q].x; o[2 * q + 1] = ov[q].y; }
;                 u32x4 w; w.x = cvt_pk_bf16(o[0], o[1]); w.y = cvt_pk_bf16(o[2], o[3]); w.z = cvt_pk_bf16(o[4], o[5]); w.w = cvt_pk_bf16(o[6], o[7]);
;                 *(u32x4*)rowp = w; }
; template <class Epi>
; DEV void gemm_phase(LAS unsigned char* lds, const int tid, const Gemm g, const StaticOrder& S, const Epi& E) {
;     ...
;             PG8_BAR; PG8_WAIT_L(0); PG8_MMA(1, 0, At, B0); PG8_BAR; PG8_SCHED;
;             PG8_STAGE(PG8_SB(1, 1), b3 + hstep, voffB);
;             PG8_WAIT_V(6); PG8_BAR; PG8_MMA(1, 1, At, B1); PG8_BAR;
;         }
	s_waitcnt lgkmcnt(0)
	s_waitcnt lgkmcnt(0)
	v_mfma_f32_16x16x32_bf16 v[62:65], v[156:159], v[172:175], v[62:65]
	v_mfma_f32_16x16x32_bf16 v[54:57], v[164:167], v[172:175], v[54:57]
	v_mfma_f32_16x16x32_bf16 v[46:49], v[156:159], v[180:183], v[46:49]
	v_mfma_f32_16x16x32_bf16 v[38:41], v[164:167], v[180:183], v[38:41]
	v_mfma_f32_16x16x32_bf16 v[30:33], v[156:159], v[198:201], v[30:33]
	v_mfma_f32_16x16x32_bf16 v[22:25], v[164:167], v[198:201], v[22:25]
	v_mfma_f32_16x16x32_bf16 v[14:17], v[156:159], v[206:209], v[14:17]
	v_mfma_f32_16x16x32_bf16 v[6:9], v[164:167], v[206:209], v[6:9]
	v_mfma_f32_16x16x32_bf16 v[62:65], v[160:163], v[176:179], v[62:65]
	v_mfma_f32_16x16x32_bf16 v[54:57], v[168:171], v[176:179], v[54:57]
	v_mfma_f32_16x16x32_bf16 v[46:49], v[160:163], v[184:187], v[46:49]
	v_mfma_f32_16x16x32_bf16 v[38:41], v[168:171], v[184:187], v[38:41]
	v_mfma_f32_16x16x32_bf16 v[30:33], v[160:163], v[202:205], v[30:33]
	v_mfma_f32_16x16x32_bf16 v[22:25], v[168:171], v[202:205], v[22:25]
	v_mfma_f32_16x16x32_bf16 v[14:17], v[160:163], v[210:213], v[14:17]
	v_mfma_f32_16x16x32_bf16 v[6:9], v[168:171], v[210:213], v[6:9]
	s_barrier
	s_add_u32 s6, s6, 0x40080
	s_addc_u32 s7, s7, 0
	s_add_i32 s26, s26, s28
	v_lshl_add_u64 v[152:153], s[6:7], 0, v[132:133]
	s_mov_b32 m0, s26
	s_nop 0
	global_load_lds_dwordx4 v[152:153], off
	v_lshl_add_u64 v[152:153], s[6:7], 0, v[136:137]
	s_add_i32 m0, s26, 0x2000
	s_nop 0
	global_load_lds_dwordx4 v[152:153], off
	s_waitcnt vmcnt(6)
	s_barrier
	v_mfma_f32_16x16x32_bf16 v[58:61], v[214:217], v[172:175], v[58:61]
	v_mfma_f32_16x16x32_bf16 v[50:53], v[222:225], v[172:175], v[50:53]
	v_mfma_f32_16x16x32_bf16 v[42:45], v[214:217], v[180:183], v[42:45]
	v_mfma_f32_16x16x32_bf16 v[34:37], v[222:225], v[180:183], v[34:37]
	v_mfma_f32_16x16x32_bf16 v[26:29], v[214:217], v[198:201], v[26:29]
	v_mfma_f32_16x16x32_bf16 v[18:21], v[222:225], v[198:201], v[18:21]
	v_mfma_f32_16x16x32_bf16 v[10:13], v[214:217], v[206:209], v[10:13]
	v_mfma_f32_16x16x32_bf16 v[2:5], v[222:225], v[206:209], v[2:5]
	v_mfma_f32_16x16x32_bf16 v[58:61], v[218:221], v[176:179], v[58:61]
	v_mfma_f32_16x16x32_bf16 v[50:53], v[226:229], v[176:179], v[50:53]
	v_mfma_f32_16x16x32_bf16 v[42:45], v[218:221], v[184:187], v[42:45]
	v_mfma_f32_16x16x32_bf16 v[34:37], v[226:229], v[184:187], v[34:37]
	v_mfma_f32_16x16x32_bf16 v[26:29], v[218:221], v[202:205], v[26:29]
	v_mfma_f32_16x16x32_bf16 v[18:21], v[226:229], v[202:205], v[18:21]
	v_mfma_f32_16x16x32_bf16 v[10:13], v[218:221], v[210:213], v[10:13]
	v_mfma_f32_16x16x32_bf16 v[2:5], v[226:229], v[210:213], v[2:5]
	s_setprio 0
	s_add_i32 s48, s48, 2
	s_add_u32 s24, s24, 0x100
	s_addc_u32 s25, s25, 0
	s_add_u32 s46, s46, 0x100
	s_addc_u32 s47, s47, 0
	s_cmp_gt_u32 s48, 13
	s_barrier
	s_cbranch_scc0 .LBB0_1252
	v_lshl_or_b32 v158, s22, 7, v154
	s_mov_b32 s22, 0xbfb8aa3b
	v_pk_mul_f32 v[162:163], v[126:127], s[22:23] op_sel_hi:[1,0]
	v_pk_mul_f32 v[164:165], v[128:129], s[22:23] op_sel_hi:[1,0]
	v_exp_f32_e32 v162, v162
	v_exp_f32_e32 v163, v163
	v_exp_f32_e32 v164, v164
	v_exp_f32_e32 v165, v165
	v_pk_mul_f32 v[166:167], v[118:119], s[22:23] op_sel_hi:[1,0]
	v_pk_add_f32 v[162:163], v[162:163], 1.0 op_sel_hi:[1,0]
	v_exp_f32_e32 v166, v166
	v_rcp_f32_e32 v162, v162
	v_rcp_f32_e32 v163, v163
	v_exp_f32_e32 v167, v167
	v_pk_mul_f32 v[168:169], v[120:121], s[22:23] op_sel_hi:[1,0]
	s_lshl_b32 s6, s44, 2
	v_pk_mul_f32 v[126:127], v[126:127], v[162:163]
	v_exp_f32_e32 v168, v168
	v_pk_mul_f32 v[122:123], v[126:127], v[122:123]
	v_pk_add_f32 v[126:127], v[164:165], 1.0 op_sel_hi:[1,0]
	v_exp_f32_e32 v169, v169
	v_rcp_f32_e32 v126, v126
	v_rcp_f32_e32 v127, v127
	s_lshl_b32 s1, s44, 8
	s_and_b32 s6, s6, 0xffffff00
	s_add_i32 s6, s6, s1
	v_pk_mul_f32 v[126:127], v[128:129], v[126:127]
	v_add_u32_e32 v156, s6, v141
	v_pk_mul_f32 v[124:125], v[126:127], v[124:125]
	v_pk_add_f32 v[126:127], v[166:167], 1.0 op_sel_hi:[1,0]
	v_ashrrev_i32_e32 v159, 31, v158
	v_rcp_f32_e32 v126, v126
	v_rcp_f32_e32 v127, v127
	v_mov_b64_e32 v[152:153], s[78:79]
	s_movk_i32 s1, 0x1600
	v_mad_i64_i32 v[160:161], s[6:7], v156, s1, v[152:153]
	v_pk_mul_f32 v[118:119], v[118:119], v[126:127]
	s_and_b64 vcc, exec, s[16:17]
	v_pk_mul_f32 v[118:119], v[118:119], v[114:115]
	v_pk_add_f32 v[114:115], v[168:169], 1.0 op_sel_hi:[1,0]
	s_mov_b32 s44, s43
	v_rcp_f32_e32 v114, v114
	v_rcp_f32_e32 v115, v115
	s_mov_b32 s45, s0
	s_mov_b32 s46, s43
	s_mov_b64 s[26:27], s[20:21]
	v_pk_mul_f32 v[114:115], v[120:121], v[114:115]
	s_mov_b32 s52, 0x800000
	v_pk_mul_f32 v[120:121], v[114:115], v[116:117]
	v_lshlrev_b64 v[114:115], 1, v[158:159]
	v_lshl_add_u64 v[126:127], v[160:161], 0, v[114:115]
	v_cvt_pk_bf16_f32 v116, v122, v123
	v_cvt_pk_bf16_f32 v117, v124, v125
	v_cvt_pk_bf16_f32 v118, v118, v119
	v_cvt_pk_bf16_f32 v119, v120, v121
	global_store_dwordx4 v[126:127], v[116:119], off
	v_pk_mul_f32 v[120:121], v[112:113], s[22:23] op_sel_hi:[1,0]
	v_pk_mul_f32 v[122:123], v[102:103], s[22:23] op_sel_hi:[1,0]
	v_pk_mul_f32 v[118:119], v[110:111], s[22:23] op_sel_hi:[1,0]
	v_exp_f32_e32 v120, v120
	v_exp_f32_e32 v118, v118
	v_exp_f32_e32 v119, v119
	v_exp_f32_e32 v121, v121
	v_exp_f32_e32 v122, v122
	v_exp_f32_e32 v123, v123
	v_pk_add_f32 v[118:119], v[118:119], 1.0 op_sel_hi:[1,0]
	v_pk_mul_f32 v[124:125], v[104:105], s[22:23] op_sel_hi:[1,0]
	v_rcp_f32_e32 v118, v118
	v_rcp_f32_e32 v119, v119
	v_exp_f32_e32 v124, v124
	v_exp_f32_e32 v125, v125
	v_or_b32_e32 v116, 16, v156
	v_pk_mul_f32 v[110:111], v[110:111], v[118:119]
	v_mad_i64_i32 v[116:117], s[6:7], v116, s1, v[152:153]
	v_pk_mul_f32 v[106:107], v[110:111], v[106:107]
; DEV unsigned cvt_pk_bf16(float lo, float hi) { unsigned r; asm volatile("v_cvt_pk_bf16_f32 %0, %1, %2" : "=v"(r) : "v"(lo), "v"(hi)); return r; }
;     DEV void operator()(const f32x4 (&acc)[2][2][4][2], const Unit& u, int wr, int wc, int fr, int fq) const {
;         const int row0 = prow(u.pm) + wr * 64 + fr; const int col0 = u.pn * HALF + wc * 32 + 8 * fq;
; #pragma unroll
;         for (int ai = 0; ai < 2; ++ai)
; #pragma unroll
;             for (int m = 0; m < 4; ++m) { bf16_t* rowp = O + (size_t)(row0 + ai * HALF + m * 16) * FH + col0;
;                 typedef float f32x2 __attribute__((ext_vector_type(2)));
;                 f32x2 gv[4], uv[4], ev[4], ov[4];
; #pragma unroll
;                 for (int q = 0; q < 4; ++q) { const int n = q >> 1, j = (q & 1) * 2; gv[q] = (f32x2){acc[ai][0][m][n][j], acc[ai][0][m][n][j + 1]}; uv[q] = (f32x2){acc[ai][1][m][n][j], acc[ai][1][m][n][j + 1]}; }
; #pragma unroll
;                 for (int q = 0; q < 4; ++q) { const f32x2 t = gv[q] * -1.44269504089f; ev[q].x = __builtin_amdgcn_exp2f(t.x); ev[q].y = __builtin_amdgcn_exp2f(t.y); }
; #pragma unroll
;                 for (int q = 0; q < 4; ++q) { const f32x2 d = ev[q] + 1.0f; f32x2 r; r.x = __builtin_amdgcn_rcpf(d.x); r.y = __builtin_amdgcn_rcpf(d.y); ov[q] = (gv[q] * r) * uv[q]; }
;                 float o[8];
; #pragma unroll
;                 for (int q = 0; q < 4; ++q) { o[2 * q] = ov[q].x; o[2 * q + 1] = ov[q].y; }
;                 u32x4 w; w.x = cvt_pk_bf16(o[0], o[1]); w.y = cvt_pk_bf16(o[2], o[3]); w.z = cvt_pk_bf16(o[4], o[5]); w.w = cvt_pk_bf16(o[6], o[7]);
;                 *(u32x4*)rowp = w; }
	v_pk_add_f32 v[110:111], v[120:121], 1.0 op_sel_hi:[1,0]
	s_nop 0
	v_rcp_f32_e32 v110, v110
	v_rcp_f32_e32 v111, v111
	s_nop 0
	v_pk_mul_f32 v[110:111], v[112:113], v[110:111]
	s_nop 0
	v_pk_mul_f32 v[108:109], v[110:111], v[108:109]
	v_pk_add_f32 v[110:111], v[122:123], 1.0 op_sel_hi:[1,0]
	s_nop 0
	v_rcp_f32_e32 v110, v110
	v_rcp_f32_e32 v111, v111
	s_nop 0
	v_pk_mul_f32 v[102:103], v[102:103], v[110:111]
	s_nop 0
	v_pk_mul_f32 v[102:103], v[102:103], v[98:99]
	v_pk_add_f32 v[98:99], v[124:125], 1.0 op_sel_hi:[1,0]
	v_lshl_add_u64 v[110:111], v[116:117], 0, v[114:115]
	v_rcp_f32_e32 v98, v98
	v_rcp_f32_e32 v99, v99
	s_nop 0
	v_pk_mul_f32 v[98:99], v[104:105], v[98:99]
	s_nop 0
	v_pk_mul_f32 v[104:105], v[98:99], v[100:101]
	v_cvt_pk_bf16_f32 v98, v106, v107
	v_cvt_pk_bf16_f32 v99, v108, v109
	v_cvt_pk_bf16_f32 v100, v102, v103
	v_pk_mul_f32 v[102:103], v[96:97], s[22:23] op_sel_hi:[1,0]
	v_cvt_pk_bf16_f32 v101, v104, v105
	global_store_dwordx4 v[110:111], v[98:101], off
	v_exp_f32_e32 v102, v102
	v_exp_f32_e32 v103, v103
	v_pk_mul_f32 v[100:101], v[94:95], s[22:23] op_sel_hi:[1,0]
	v_pk_mul_f32 v[104:105], v[86:87], s[22:23] op_sel_hi:[1,0]
	v_exp_f32_e32 v100, v100
	v_exp_f32_e32 v101, v101
	v_exp_f32_e32 v104, v104
	v_exp_f32_e32 v105, v105
	v_pk_mul_f32 v[106:107], v[88:89], s[22:23] op_sel_hi:[1,0]
	v_pk_add_f32 v[100:101], v[100:101], 1.0 op_sel_hi:[1,0]
	v_exp_f32_e32 v106, v106
	v_rcp_f32_e32 v100, v100
	v_rcp_f32_e32 v101, v101
	v_exp_f32_e32 v107, v107
	v_or_b32_e32 v98, 32, v156
	v_mad_i64_i32 v[98:99], s[6:7], v98, s1, v[152:153]
	v_pk_mul_f32 v[94:95], v[94:95], v[100:101]
	s_nop 0
	v_pk_mul_f32 v[90:91], v[94:95], v[90:91]
	v_pk_add_f32 v[94:95], v[102:103], 1.0 op_sel_hi:[1,0]
	s_nop 0
	v_rcp_f32_e32 v94, v94
	v_rcp_f32_e32 v95, v95
	s_nop 0
	v_pk_mul_f32 v[94:95], v[96:97], v[94:95]
	s_nop 0
	v_pk_mul_f32 v[92:93], v[94:95], v[92:93]
	v_pk_add_f32 v[94:95], v[104:105], 1.0 op_sel_hi:[1,0]
	s_nop 0
	v_rcp_f32_e32 v94, v94
	v_rcp_f32_e32 v95, v95
	s_nop 0
	v_pk_mul_f32 v[86:87], v[86:87], v[94:95]
	s_nop 0
	v_pk_mul_f32 v[86:87], v[86:87], v[82:83]
	v_pk_add_f32 v[82:83], v[106:107], 1.0 op_sel_hi:[1,0]
	v_lshl_add_u64 v[94:95], v[98:99], 0, v[114:115]
	v_rcp_f32_e32 v82, v82
	v_rcp_f32_e32 v83, v83
	s_nop 0
	v_pk_mul_f32 v[82:83], v[88:89], v[82:83]
	s_nop 0
	v_pk_mul_f32 v[88:89], v[82:83], v[84:85]
	v_cvt_pk_bf16_f32 v82, v90, v91
	v_cvt_pk_bf16_f32 v83, v92, v93
	v_cvt_pk_bf16_f32 v84, v86, v87
	v_pk_mul_f32 v[86:87], v[80:81], s[22:23] op_sel_hi:[1,0]
	v_cvt_pk_bf16_f32 v85, v88, v89
	global_store_dwordx4 v[94:95], v[82:85], off
	v_exp_f32_e32 v86, v86
	v_exp_f32_e32 v87, v87
	v_pk_mul_f32 v[84:85], v[78:79], s[22:23] op_sel_hi:[1,0]
	v_pk_mul_f32 v[88:89], v[70:71], s[22:23] op_sel_hi:[1,0]
	v_exp_f32_e32 v84, v84
	v_exp_f32_e32 v85, v85
	v_exp_f32_e32 v88, v88
	v_exp_f32_e32 v89, v89
	v_pk_mul_f32 v[90:91], v[72:73], s[22:23] op_sel_hi:[1,0]
	v_pk_add_f32 v[84:85], v[84:85], 1.0 op_sel_hi:[1,0]
	v_exp_f32_e32 v90, v90
	v_rcp_f32_e32 v84, v84
	v_rcp_f32_e32 v85, v85
	v_exp_f32_e32 v91, v91
	v_or_b32_e32 v82, 48, v156
	v_mad_i64_i32 v[82:83], s[6:7], v82, s1, v[152:153]
	v_pk_mul_f32 v[78:79], v[78:79], v[84:85]
	s_nop 0
	v_pk_mul_f32 v[74:75], v[78:79], v[74:75]
	v_pk_add_f32 v[78:79], v[86:87], 1.0 op_sel_hi:[1,0]
	s_nop 0
	v_rcp_f32_e32 v78, v78
	v_rcp_f32_e32 v79, v79
	s_nop 0
	v_pk_mul_f32 v[78:79], v[80:81], v[78:79]
	s_nop 0
	v_pk_mul_f32 v[76:77], v[78:79], v[76:77]
	v_pk_add_f32 v[78:79], v[88:89], 1.0 op_sel_hi:[1,0]
	s_nop 0
	v_rcp_f32_e32 v78, v78
	v_rcp_f32_e32 v79, v79
	s_nop 0
	v_pk_mul_f32 v[70:71], v[70:71], v[78:79]
	s_nop 0
	v_pk_mul_f32 v[70:71], v[70:71], v[66:67]
	v_pk_add_f32 v[66:67], v[90:91], 1.0 op_sel_hi:[1,0]
	v_lshl_add_u64 v[78:79], v[82:83], 0, v[114:115]
	v_rcp_f32_e32 v66, v66
	v_rcp_f32_e32 v67, v67
	s_nop 0
	v_pk_mul_f32 v[66:67], v[72:73], v[66:67]
	s_nop 0
	v_pk_mul_f32 v[72:73], v[66:67], v[68:69]
	v_cvt_pk_bf16_f32 v66, v74, v75
	v_cvt_pk_bf16_f32 v67, v76, v77
	v_cvt_pk_bf16_f32 v68, v70, v71
	v_pk_mul_f32 v[70:71], v[64:65], s[22:23] op_sel_hi:[1,0]
	v_cvt_pk_bf16_f32 v69, v72, v73
	global_store_dwordx4 v[78:79], v[66:69], off
	v_exp_f32_e32 v70, v70
	v_exp_f32_e32 v71, v71
	v_pk_mul_f32 v[68:69], v[62:63], s[22:23] op_sel_hi:[1,0]
	v_pk_mul_f32 v[72:73], v[54:55], s[22:23] op_sel_hi:[1,0]
	v_exp_f32_e32 v68, v68
	v_exp_f32_e32 v69, v69
	v_exp_f32_e32 v72, v72
	v_exp_f32_e32 v73, v73
	v_pk_mul_f32 v[74:75], v[56:57], s[22:23] op_sel_hi:[1,0]
	v_pk_add_f32 v[68:69], v[68:69], 1.0 op_sel_hi:[1,0]
	v_exp_f32_e32 v74, v74
	v_rcp_f32_e32 v68, v68
	v_rcp_f32_e32 v69, v69
	v_exp_f32_e32 v75, v75
	v_add_u32_e32 v66, 0x80, v156
	v_mad_i64_i32 v[66:67], s[6:7], v66, s1, v[152:153]
	v_pk_mul_f32 v[62:63], v[62:63], v[68:69]
	s_nop 0
	v_pk_mul_f32 v[58:59], v[62:63], v[58:59]
	v_pk_add_f32 v[62:63], v[70:71], 1.0 op_sel_hi:[1,0]
	s_nop 0
	v_rcp_f32_e32 v62, v62
	v_rcp_f32_e32 v63, v63
	s_nop 0
	v_pk_mul_f32 v[62:63], v[64:65], v[62:63]
	s_nop 0
	v_pk_mul_f32 v[60:61], v[62:63], v[60:61]
	v_pk_add_f32 v[62:63], v[72:73], 1.0 op_sel_hi:[1,0]
	s_nop 0
	v_rcp_f32_e32 v62, v62
	v_rcp_f32_e32 v63, v63
	s_nop 0
	v_pk_mul_f32 v[54:55], v[54:55], v[62:63]
	s_nop 0
	v_pk_mul_f32 v[54:55], v[54:55], v[50:51]
; DEV unsigned cvt_pk_bf16(float lo, float hi) { unsigned r; asm volatile("v_cvt_pk_bf16_f32 %0, %1, %2" : "=v"(r) : "v"(lo), "v"(hi)); return r; }
; #define PG8_WAIT_V(n) asm volatile("s_waitcnt vmcnt(" #n ")" ::: "memory")
; #define PG8_BAR __builtin_amdgcn_s_barrier()
;     DEV void operator()(const f32x4 (&acc)[2][2][4][2], const Unit& u, int wr, int wc, int fr, int fq) const {
;         const int row0 = prow(u.pm) + wr * 64 + fr; const int col0 = u.pn * HALF + wc * 32 + 8 * fq;
; #pragma unroll
;         for (int ai = 0; ai < 2; ++ai)
; #pragma unroll
;             for (int m = 0; m < 4; ++m) { bf16_t* rowp = O + (size_t)(row0 + ai * HALF + m * 16) * FH + col0;
;                 typedef float f32x2 __attribute__((ext_vector_type(2)));
;                 f32x2 gv[4], uv[4], ev[4], ov[4];
; #pragma unroll
;                 for (int q = 0; q < 4; ++q) { const int n = q >> 1, j = (q & 1) * 2; gv[q] = (f32x2){acc[ai][0][m][n][j], acc[ai][0][m][n][j + 1]}; uv[q] = (f32x2){acc[ai][1][m][n][j], acc[ai][1][m][n][j + 1]}; }
; #pragma unroll
;                 for (int q = 0; q < 4; ++q) { const f32x2 t = gv[q] * -1.44269504089f; ev[q].x = __builtin_amdgcn_exp2f(t.x); ev[q].y = __builtin_amdgcn_exp2f(t.y); }
; #pragma unroll
;                 for (int q = 0; q < 4; ++q) { const f32x2 d = ev[q] + 1.0f; f32x2 r; r.x = __builtin_amdgcn_rcpf(d.x); r.y = __builtin_amdgcn_rcpf(d.y); ov[q] = (gv[q] * r) * uv[q]; }
;                 float o[8];
; #pragma unroll
;                 for (int q = 0; q < 4; ++q) { o[2 * q] = ov[q].x; o[2 * q + 1] = ov[q].y; }
;                 u32x4 w; w.x = cvt_pk_bf16(o[0], o[1]); w.y = cvt_pk_bf16(o[2], o[3]); w.z = cvt_pk_bf16(o[4], o[5]); w.w = cvt_pk_bf16(o[6], o[7]);
;                 *(u32x4*)rowp = w; }
; template <class Epi>
; DEV void gemm_phase(LAS unsigned char* lds, const int tid, const Gemm g, const StaticOrder& S, const Epi& E) {
;     ...
;         E(acc, cur, wr, wc, fr, fq);
;         if (!has_next) break;
; #pragma unroll
;         for (int a = 0; a < 2; ++a)
; #pragma unroll
;             for (int b = 0; b < 2; ++b)
; #pragma unroll
;                 for (int m = 0; m < 4; ++m)
; #pragma unroll
;                     for (int n = 0; n < 2; ++n) acc[a][b][m][n] = (f32x4){0.f, 0.f, 0.f, 0.f};
;         cur = nxt; cA = nA; cB = nB; ++ui;
;     }
;     PG8_WAIT_V(0);
;     if (wr == 0) PG8_BAR;
;     PG8_BAR;
	v_pk_add_f32 v[50:51], v[74:75], 1.0 op_sel_hi:[1,0]
	v_lshl_add_u64 v[62:63], v[66:67], 0, v[114:115]
	v_rcp_f32_e32 v50, v50
	v_rcp_f32_e32 v51, v51
	s_nop 0
	v_pk_mul_f32 v[50:51], v[56:57], v[50:51]
	s_nop 0
	v_pk_mul_f32 v[56:57], v[50:51], v[52:53]
	v_cvt_pk_bf16_f32 v50, v58, v59
	v_cvt_pk_bf16_f32 v51, v60, v61
	v_cvt_pk_bf16_f32 v52, v54, v55
	v_pk_mul_f32 v[54:55], v[48:49], s[22:23] op_sel_hi:[1,0]
	v_cvt_pk_bf16_f32 v53, v56, v57
	global_store_dwordx4 v[62:63], v[50:53], off
	v_exp_f32_e32 v54, v54
	v_exp_f32_e32 v55, v55
	v_pk_mul_f32 v[52:53], v[46:47], s[22:23] op_sel_hi:[1,0]
	v_pk_mul_f32 v[56:57], v[38:39], s[22:23] op_sel_hi:[1,0]
	v_exp_f32_e32 v52, v52
	v_exp_f32_e32 v53, v53
	v_exp_f32_e32 v56, v56
	v_exp_f32_e32 v57, v57
	v_pk_mul_f32 v[58:59], v[40:41], s[22:23] op_sel_hi:[1,0]
	v_pk_add_f32 v[52:53], v[52:53], 1.0 op_sel_hi:[1,0]
	v_exp_f32_e32 v58, v58
	v_rcp_f32_e32 v52, v52
	v_rcp_f32_e32 v53, v53
	v_exp_f32_e32 v59, v59
	v_add_u32_e32 v50, 0x90, v156
	v_mad_i64_i32 v[50:51], s[6:7], v50, s1, v[152:153]
	v_pk_mul_f32 v[46:47], v[46:47], v[52:53]
	s_nop 0
	v_pk_mul_f32 v[42:43], v[46:47], v[42:43]
	v_pk_add_f32 v[46:47], v[54:55], 1.0 op_sel_hi:[1,0]
	s_nop 0
	v_rcp_f32_e32 v46, v46
	v_rcp_f32_e32 v47, v47
	s_nop 0
	v_pk_mul_f32 v[46:47], v[48:49], v[46:47]
	s_nop 0
	v_pk_mul_f32 v[44:45], v[46:47], v[44:45]
	v_pk_add_f32 v[46:47], v[56:57], 1.0 op_sel_hi:[1,0]
	s_nop 0
	v_rcp_f32_e32 v46, v46
	v_rcp_f32_e32 v47, v47
	s_nop 0
	v_pk_mul_f32 v[38:39], v[38:39], v[46:47]
	s_nop 0
	v_pk_mul_f32 v[38:39], v[38:39], v[34:35]
	v_pk_add_f32 v[34:35], v[58:59], 1.0 op_sel_hi:[1,0]
	v_lshl_add_u64 v[46:47], v[50:51], 0, v[114:115]
	v_rcp_f32_e32 v34, v34
	v_rcp_f32_e32 v35, v35
	s_nop 0
	v_pk_mul_f32 v[34:35], v[40:41], v[34:35]
	s_nop 0
	v_pk_mul_f32 v[40:41], v[34:35], v[36:37]
	v_cvt_pk_bf16_f32 v34, v42, v43
	v_cvt_pk_bf16_f32 v35, v44, v45
	v_cvt_pk_bf16_f32 v36, v38, v39
	v_pk_mul_f32 v[38:39], v[32:33], s[22:23] op_sel_hi:[1,0]
	v_cvt_pk_bf16_f32 v37, v40, v41
	global_store_dwordx4 v[46:47], v[34:37], off
	v_exp_f32_e32 v38, v38
	v_exp_f32_e32 v39, v39
	v_pk_mul_f32 v[36:37], v[30:31], s[22:23] op_sel_hi:[1,0]
	v_pk_mul_f32 v[40:41], v[22:23], s[22:23] op_sel_hi:[1,0]
	v_exp_f32_e32 v36, v36
	v_exp_f32_e32 v37, v37
	v_exp_f32_e32 v40, v40
	v_exp_f32_e32 v41, v41
	v_pk_mul_f32 v[42:43], v[24:25], s[22:23] op_sel_hi:[1,0]
	v_pk_add_f32 v[36:37], v[36:37], 1.0 op_sel_hi:[1,0]
	v_exp_f32_e32 v42, v42
	v_rcp_f32_e32 v36, v36
	v_rcp_f32_e32 v37, v37
	v_exp_f32_e32 v43, v43
	v_add_u32_e32 v34, 0xa0, v156
	v_mad_i64_i32 v[34:35], s[6:7], v34, s1, v[152:153]
	v_pk_mul_f32 v[30:31], v[30:31], v[36:37]
	s_nop 0
	v_pk_mul_f32 v[26:27], v[30:31], v[26:27]
	v_pk_add_f32 v[30:31], v[38:39], 1.0 op_sel_hi:[1,0]
	s_nop 0
	v_rcp_f32_e32 v30, v30
	v_rcp_f32_e32 v31, v31
	s_nop 0
	v_pk_mul_f32 v[30:31], v[32:33], v[30:31]
	s_nop 0
	v_pk_mul_f32 v[28:29], v[30:31], v[28:29]
	v_pk_add_f32 v[30:31], v[40:41], 1.0 op_sel_hi:[1,0]
	s_nop 0
	v_rcp_f32_e32 v30, v30
	v_rcp_f32_e32 v31, v31
	s_nop 0
	v_pk_mul_f32 v[22:23], v[22:23], v[30:31]
	s_nop 0
	v_pk_mul_f32 v[22:23], v[22:23], v[18:19]
	v_pk_add_f32 v[18:19], v[42:43], 1.0 op_sel_hi:[1,0]
	v_lshl_add_u64 v[30:31], v[34:35], 0, v[114:115]
	v_rcp_f32_e32 v18, v18
	v_rcp_f32_e32 v19, v19
	s_nop 0
	v_pk_mul_f32 v[18:19], v[24:25], v[18:19]
	s_nop 0
	v_pk_mul_f32 v[24:25], v[18:19], v[20:21]
	v_cvt_pk_bf16_f32 v18, v26, v27
	v_cvt_pk_bf16_f32 v19, v28, v29
	v_cvt_pk_bf16_f32 v20, v22, v23
	v_pk_mul_f32 v[22:23], v[16:17], s[22:23] op_sel_hi:[1,0]
	v_cvt_pk_bf16_f32 v21, v24, v25
	global_store_dwordx4 v[30:31], v[18:21], off
	v_exp_f32_e32 v22, v22
	v_exp_f32_e32 v23, v23
	v_pk_mul_f32 v[20:21], v[14:15], s[22:23] op_sel_hi:[1,0]
	v_pk_mul_f32 v[24:25], v[6:7], s[22:23] op_sel_hi:[1,0]
	v_exp_f32_e32 v20, v20
	v_exp_f32_e32 v21, v21
	v_exp_f32_e32 v24, v24
	v_exp_f32_e32 v25, v25
	v_pk_mul_f32 v[26:27], v[8:9], s[22:23] op_sel_hi:[1,0]
	v_pk_add_f32 v[20:21], v[20:21], 1.0 op_sel_hi:[1,0]
	v_exp_f32_e32 v26, v26
	v_rcp_f32_e32 v20, v20
	v_rcp_f32_e32 v21, v21
	v_exp_f32_e32 v27, v27
	v_add_u32_e32 v18, 0xb0, v156
	v_mad_i64_i32 v[18:19], s[6:7], v18, s1, v[152:153]
	v_pk_mul_f32 v[14:15], v[14:15], v[20:21]
	s_mov_b32 s22, s0
	v_pk_mul_f32 v[10:11], v[14:15], v[10:11]
	v_pk_add_f32 v[14:15], v[22:23], 1.0 op_sel_hi:[1,0]
	s_mov_b64 s[6:7], s[18:19]
	v_rcp_f32_e32 v14, v14
	v_rcp_f32_e32 v15, v15
	s_nop 0
	v_pk_mul_f32 v[14:15], v[16:17], v[14:15]
	s_nop 0
	v_pk_mul_f32 v[12:13], v[14:15], v[12:13]
	v_pk_add_f32 v[14:15], v[24:25], 1.0 op_sel_hi:[1,0]
	s_nop 0
	v_rcp_f32_e32 v14, v14
	v_rcp_f32_e32 v15, v15
	s_nop 0
	v_pk_mul_f32 v[6:7], v[6:7], v[14:15]
	s_nop 0
	v_pk_mul_f32 v[6:7], v[6:7], v[2:3]
	v_pk_add_f32 v[2:3], v[26:27], 1.0 op_sel_hi:[1,0]
	v_lshl_add_u64 v[14:15], v[18:19], 0, v[114:115]
	v_rcp_f32_e32 v2, v2
	v_rcp_f32_e32 v3, v3
	s_nop 0
	v_pk_mul_f32 v[2:3], v[8:9], v[2:3]
	s_nop 0
	v_pk_mul_f32 v[8:9], v[2:3], v[4:5]
	v_cvt_pk_bf16_f32 v2, v10, v11
	v_cvt_pk_bf16_f32 v3, v12, v13
	v_cvt_pk_bf16_f32 v4, v6, v7
	s_nop 0
	v_cvt_pk_bf16_f32 v5, v8, v9
	global_store_dwordx4 v[14:15], v[2:5], off
	s_cbranch_vccz .LBB0_1242
	s_waitcnt vmcnt(0)
	s_cmpk_gt_u32 s15, 0xff
	s_cbranch_scc1 .LBB0_1256
	s_barrier

; #define PG8_STAGE(bufoff, gbase, voff) do { _Pragma("unroll") for (int _i = 0; _i < 2; ++_i) \
;         __builtin_amdgcn_global_load_lds((const unsigned*)((const char*)(gbase) + (voff)[_i]), (LAS unsigned*)(lds + (bufoff) + ldsw + _i * 8192), 16, 0, 0); } while (0)
; #define PG8_LDA(dst, b, h) do { _Pragma("unroll") for (int m = 0; m < 4; ++m) _Pragma("unroll") for (int k = 0; k < 2; ++k) dst[m][k] = *(const LAS bf16x8*)(lds + PG8_SA(b, h) + aoff + m * 2048 + k * 1024); } while (0)
; #define PG8_LDB(dst, b, h) do { _Pragma("unroll") for (int n = 0; n < 2; ++n) _Pragma("unroll") for (int k = 0; k < 2; ++k) dst[n][k] = *(const LAS bf16x8*)(lds + PG8_SB(b, h) + boff + n * 2048 + k * 1024); } while (0)
; #define PG8_MMA(ai, bj, At, Bt) do { __builtin_amdgcn_s_setprio(1); _Pragma("unroll") for (int m = 0; m < 4; ++m) _Pragma("unroll") for (int n = 0; n < 2; ++n) _Pragma("unroll") for (int k = 0; k < 2; ++k) \
;         acc[ai][bj][m][n] = __builtin_amdgcn_mfma_f32_16x16x32_bf16(Bt[n][k], At[m][k], acc[ai][bj][m][n], 0, 0, 0); __builtin_amdgcn_s_setprio(0); } while (0)
; #define PG8_WAIT_L(n) asm volatile("s_waitcnt lgkmcnt(" #n ")" ::: "memory")
; #define PG8_BAR __builtin_amdgcn_s_barrier()
; #define PG8_SCHED __builtin_amdgcn_sched_barrier(0)
; template <class Epi>
; DEV void gemm_phase(LAS unsigned char* lds, const int tid, const Gemm g, const StaticOrder& S, const Epi& E) {
;     ...
;         for (int t = 0; t < nt; t += 2) {
;             const bool last = (t == nt - 2);
;             const char* a1 = cA + (size_t)(t + 1) * kstep;
;             const char* a2 = last ? nA : cA + (size_t)(t + 2) * kstep; const char* b2 = last ? nB : cB + (size_t)(t + 2) * kstep;
;             const char* a3 = a2 + kstep; const char* b3 = b2 + kstep;
;             PG8_LDB(B0, 0, 0); PG8_SCHED; PG8_LDA(At, 0, 0); PG8_STAGE(PG8_SA(1, 1), a1 + hstep, voffA);
;             PG8_WAIT_L(8); PG8_BAR; PG8_WAIT_L(0); PG8_MMA(0, 0, At, B0); PG8_BAR; PG8_SCHED;
;             PG8_LDB(B1, 0, 1); PG8_STAGE(PG8_SB(0, 0), b2, voffB);
;             PG8_BAR; PG8_WAIT_L(0); PG8_MMA(0, 1, At, B1); PG8_BAR;
;             PG8_LDA(At, 0, 1); PG8_STAGE(PG8_SA(0, 0), a2, voffA);
;             PG8_BAR; PG8_WAIT_L(0); PG8_MMA(1, 0, At, B0); PG8_BAR; PG8_SCHED;
.Lprio_skip_3:
	s_add_u32 s22, s20, 0x100
	s_addc_u32 s23, s21, 0
	s_add_i32 s49, 0, 0x10000
	v_add_u32_e32 v152, s49, v1
	ds_read_b128 v[156:159], v152
	ds_read_b128 v[160:163], v152 offset:1024
	ds_read_b128 v[164:167], v152 offset:2048
	ds_read_b128 v[168:171], v152 offset:3072
	s_cmp_eq_u32 s48, 40
	s_cselect_b32 s25, s3, s23
	s_cselect_b32 s24, s2, s22
	s_cselect_b32 s7, s19, s47
	s_cselect_b32 s6, s18, s46
	v_lshl_add_u64 v[152:153], s[20:21], 0, v[138:139]
	s_add_i32 m0, s27, 0xc000
	ds_read_b128 v[172:175], v155
	ds_read_b128 v[176:179], v155 offset:1024
	ds_read_b128 v[180:183], v155 offset:2048
	ds_read_b128 v[184:187], v155 offset:3072
	ds_read_b128 v[198:201], v155 offset:4096
	ds_read_b128 v[202:205], v155 offset:5120
	ds_read_b128 v[206:209], v155 offset:6144
	ds_read_b128 v[210:213], v155 offset:7168
	global_load_lds_dwordx4 v[152:153], off
	v_lshl_add_u64 v[152:153], s[20:21], 0, v[150:151]
	s_add_i32 m0, s27, 0xe000
	s_nop 0
	global_load_lds_dwordx4 v[152:153], off
	s_waitcnt lgkmcnt(8)
	s_barrier
	s_waitcnt lgkmcnt(0)
	s_waitcnt lgkmcnt(0)
	v_mfma_f32_16x16x32_bf16 v[126:129], v[156:159], v[172:175], v[126:129]
	v_mfma_f32_16x16x32_bf16 v[122:125], v[164:167], v[172:175], v[122:125]
	v_mfma_f32_16x16x32_bf16 v[118:121], v[156:159], v[180:183], v[118:121]
	v_mfma_f32_16x16x32_bf16 v[110:113], v[164:167], v[180:183], v[110:113]
	v_mfma_f32_16x16x32_bf16 v[102:105], v[156:159], v[198:201], v[102:105]
	v_mfma_f32_16x16x32_bf16 v[94:97], v[164:167], v[198:201], v[94:97]
	v_mfma_f32_16x16x32_bf16 v[86:89], v[156:159], v[206:209], v[86:89]
	v_mfma_f32_16x16x32_bf16 v[78:81], v[164:167], v[206:209], v[78:81]
	v_mfma_f32_16x16x32_bf16 v[126:129], v[160:163], v[176:179], v[126:129]
	v_mfma_f32_16x16x32_bf16 v[122:125], v[168:171], v[176:179], v[122:125]
	v_mfma_f32_16x16x32_bf16 v[118:121], v[160:163], v[184:187], v[118:121]
	v_mfma_f32_16x16x32_bf16 v[110:113], v[168:171], v[184:187], v[110:113]
	v_mfma_f32_16x16x32_bf16 v[102:105], v[160:163], v[202:205], v[102:105]
	v_mfma_f32_16x16x32_bf16 v[94:97], v[168:171], v[202:205], v[94:97]
	v_mfma_f32_16x16x32_bf16 v[86:89], v[160:163], v[210:213], v[86:89]
	v_mfma_f32_16x16x32_bf16 v[78:81], v[168:171], v[210:213], v[78:81]
	s_barrier
	s_add_i32 s50, 0, 0x14000
	v_add_u32_e32 v152, s50, v1
	s_add_i32 s20, s49, s26
	ds_read_b128 v[214:217], v152
	ds_read_b128 v[218:221], v152 offset:1024
	ds_read_b128 v[222:225], v152 offset:2048
	ds_read_b128 v[226:229], v152 offset:3072
	v_lshl_add_u64 v[152:153], s[6:7], 0, v[132:133]
	s_mov_b32 m0, s20
	v_lshl_add_u64 v[230:231], s[6:7], 0, v[136:137]
	global_load_lds_dwordx4 v[152:153], off
	s_add_i32 m0, s20, 0x2000
	s_nop 0
	global_load_lds_dwordx4 v[230:231], off
	s_barrier
	s_waitcnt lgkmcnt(0)
	s_waitcnt lgkmcnt(0)
	v_mfma_f32_16x16x32_bf16 v[114:117], v[214:217], v[172:175], v[114:117]
	v_mfma_f32_16x16x32_bf16 v[106:109], v[222:225], v[172:175], v[106:109]
	v_mfma_f32_16x16x32_bf16 v[98:101], v[214:217], v[180:183], v[98:101]
	v_mfma_f32_16x16x32_bf16 v[90:93], v[222:225], v[180:183], v[90:93]
	v_mfma_f32_16x16x32_bf16 v[82:85], v[214:217], v[198:201], v[82:85]
	v_mfma_f32_16x16x32_bf16 v[74:77], v[222:225], v[198:201], v[74:77]
	v_mfma_f32_16x16x32_bf16 v[70:73], v[214:217], v[206:209], v[70:73]
	v_mfma_f32_16x16x32_bf16 v[66:69], v[222:225], v[206:209], v[66:69]
	v_mfma_f32_16x16x32_bf16 v[114:117], v[218:221], v[176:179], v[114:117]
	v_mfma_f32_16x16x32_bf16 v[106:109], v[226:229], v[176:179], v[106:109]
	v_mfma_f32_16x16x32_bf16 v[98:101], v[218:221], v[184:187], v[98:101]
	v_mfma_f32_16x16x32_bf16 v[90:93], v[226:229], v[184:187], v[90:93]
	v_mfma_f32_16x16x32_bf16 v[82:85], v[218:221], v[202:205], v[82:85]
	v_mfma_f32_16x16x32_bf16 v[74:77], v[226:229], v[202:205], v[74:77]
	v_mfma_f32_16x16x32_bf16 v[70:73], v[218:221], v[210:213], v[70:73]
	v_mfma_f32_16x16x32_bf16 v[66:69], v[226:229], v[210:213], v[66:69]
	s_mov_b32 m0, s27
	v_lshl_add_u64 v[232:233], s[24:25], 0, v[130:131]
	s_barrier
	ds_read_b128 v[172:175], v155 offset:16384
	ds_read_b128 v[176:179], v155 offset:17408
	ds_read_b128 v[180:183], v155 offset:18432
	ds_read_b128 v[184:187], v155 offset:19456
	ds_read_b128 v[198:201], v155 offset:20480
	ds_read_b128 v[202:205], v155 offset:21504
	ds_read_b128 v[206:209], v155 offset:22528
	ds_read_b128 v[210:213], v155 offset:23552
	global_load_lds_dwordx4 v[232:233], off
	v_lshl_add_u64 v[234:235], s[24:25], 0, v[134:135]
	s_mov_b32 m0, s28
	s_nop 0
	global_load_lds_dwordx4 v[234:235], off
	s_barrier
	s_waitcnt lgkmcnt(0)
	s_waitcnt lgkmcnt(0)
	v_mfma_f32_16x16x32_bf16 v[62:65], v[156:159], v[172:175], v[62:65]
	v_mfma_f32_16x16x32_bf16 v[58:61], v[164:167], v[172:175], v[58:61]
	v_mfma_f32_16x16x32_bf16 v[54:57], v[156:159], v[180:183], v[54:57]
	v_mfma_f32_16x16x32_bf16 v[46:49], v[164:167], v[180:183], v[46:49]
	v_mfma_f32_16x16x32_bf16 v[38:41], v[156:159], v[198:201], v[38:41]
	v_mfma_f32_16x16x32_bf16 v[30:33], v[164:167], v[198:201], v[30:33]
	v_mfma_f32_16x16x32_bf16 v[22:25], v[156:159], v[206:209], v[22:25]
	v_mfma_f32_16x16x32_bf16 v[14:17], v[164:167], v[206:209], v[14:17]
	v_mfma_f32_16x16x32_bf16 v[62:65], v[160:163], v[176:179], v[62:65]
	v_mfma_f32_16x16x32_bf16 v[58:61], v[168:171], v[176:179], v[58:61]
	v_mfma_f32_16x16x32_bf16 v[54:57], v[160:163], v[184:187], v[54:57]
	v_mfma_f32_16x16x32_bf16 v[46:49], v[168:171], v[184:187], v[46:49]
	v_mfma_f32_16x16x32_bf16 v[38:41], v[160:163], v[202:205], v[38:41]
	v_mfma_f32_16x16x32_bf16 v[30:33], v[168:171], v[202:205], v[30:33]
	v_mfma_f32_16x16x32_bf16 v[22:25], v[160:163], v[210:213], v[22:25]
	v_mfma_f32_16x16x32_bf16 v[14:17], v[168:171], v[210:213], v[14:17]
	s_barrier
; #define PG8_STAGE(bufoff, gbase, voff) do { _Pragma("unroll") for (int _i = 0; _i < 2; ++_i) \
;         __builtin_amdgcn_global_load_lds((const unsigned*)((const char*)(gbase) + (voff)[_i]), (LAS unsigned*)(lds + (bufoff) + ldsw + _i * 8192), 16, 0, 0); } while (0)
; #define PG8_LDA(dst, b, h) do { _Pragma("unroll") for (int m = 0; m < 4; ++m) _Pragma("unroll") for (int k = 0; k < 2; ++k) dst[m][k] = *(const LAS bf16x8*)(lds + PG8_SA(b, h) + aoff + m * 2048 + k * 1024); } while (0)
; #define PG8_LDB(dst, b, h) do { _Pragma("unroll") for (int n = 0; n < 2; ++n) _Pragma("unroll") for (int k = 0; k < 2; ++k) dst[n][k] = *(const LAS bf16x8*)(lds + PG8_SB(b, h) + boff + n * 2048 + k * 1024); } while (0)
; #define PG8_MMA(ai, bj, At, Bt) do { __builtin_amdgcn_s_setprio(1); _Pragma("unroll") for (int m = 0; m < 4; ++m) _Pragma("unroll") for (int n = 0; n < 2; ++n) _Pragma("unroll") for (int k = 0; k < 2; ++k) \
;         acc[ai][bj][m][n] = __builtin_amdgcn_mfma_f32_16x16x32_bf16(Bt[n][k], At[m][k], acc[ai][bj][m][n], 0, 0, 0); __builtin_amdgcn_s_setprio(0); } while (0)
; #define PG8_WAIT_V(n) asm volatile("s_waitcnt vmcnt(" #n ")" ::: "memory")
; #define PG8_WAIT_L(n) asm volatile("s_waitcnt lgkmcnt(" #n ")" ::: "memory")
; #define PG8_BAR __builtin_amdgcn_s_barrier()
; #define PG8_SCHED __builtin_amdgcn_sched_barrier(0)
; template <class Epi>
; DEV void gemm_phase(LAS unsigned char* lds, const int tid, const Gemm g, const StaticOrder& S, const Epi& E) {
;     ...
;             PG8_BAR; PG8_WAIT_L(0); PG8_MMA(1, 0, At, B0); PG8_BAR; PG8_SCHED;
;             PG8_STAGE(PG8_SB(0, 1), b2 + hstep, voffB);
;             PG8_WAIT_V(6); PG8_BAR; PG8_MMA(1, 1, At, B1); PG8_BAR;
;             PG8_LDB(B0, 1, 0); PG8_SCHED; PG8_LDA(At, 1, 0); PG8_STAGE(PG8_SA(0, 1), a2 + hstep, voffA);
;             PG8_WAIT_L(8); PG8_BAR; PG8_WAIT_L(0); PG8_MMA(0, 0, At, B0); PG8_BAR; PG8_SCHED;
;             PG8_LDB(B1, 1, 1); PG8_STAGE(PG8_SB(1, 0), b3, voffB);
;             PG8_BAR; PG8_WAIT_L(0); PG8_MMA(0, 1, At, B1); PG8_BAR;
;             PG8_LDA(At, 1, 1); PG8_STAGE(PG8_SA(1, 0), a3, voffA);
;             PG8_BAR; PG8_WAIT_L(0); PG8_MMA(1, 0, At, B0); PG8_BAR; PG8_SCHED;
	s_add_u32 s20, s6, 0xb0000
	s_addc_u32 s21, s7, 0
	s_add_i32 s49, s50, s26
	v_lshl_add_u64 v[156:157], s[20:21], 0, v[132:133]
	s_mov_b32 m0, s49
	s_nop 0
	global_load_lds_dwordx4 v[156:157], off
	v_lshl_add_u64 v[156:157], s[20:21], 0, v[136:137]
	s_add_i32 m0, s49, 0x2000
	s_nop 0
	global_load_lds_dwordx4 v[156:157], off
	s_waitcnt vmcnt(6)
	s_barrier
	v_mfma_f32_16x16x32_bf16 v[50:53], v[214:217], v[172:175], v[50:53]
	v_mfma_f32_16x16x32_bf16 v[42:45], v[222:225], v[172:175], v[42:45]
	v_mfma_f32_16x16x32_bf16 v[34:37], v[214:217], v[180:183], v[34:37]
	v_mfma_f32_16x16x32_bf16 v[26:29], v[222:225], v[180:183], v[26:29]
	v_mfma_f32_16x16x32_bf16 v[18:21], v[214:217], v[198:201], v[18:21]
	v_mfma_f32_16x16x32_bf16 v[10:13], v[222:225], v[198:201], v[10:13]
	v_mfma_f32_16x16x32_bf16 v[6:9], v[214:217], v[206:209], v[6:9]
	v_mfma_f32_16x16x32_bf16 v[2:5], v[222:225], v[206:209], v[2:5]
	v_mfma_f32_16x16x32_bf16 v[50:53], v[218:221], v[176:179], v[50:53]
	v_mfma_f32_16x16x32_bf16 v[42:45], v[226:229], v[176:179], v[42:45]
	v_mfma_f32_16x16x32_bf16 v[34:37], v[218:221], v[184:187], v[34:37]
	v_mfma_f32_16x16x32_bf16 v[26:29], v[226:229], v[184:187], v[26:29]
	v_mfma_f32_16x16x32_bf16 v[18:21], v[218:221], v[202:205], v[18:21]
	v_mfma_f32_16x16x32_bf16 v[10:13], v[226:229], v[202:205], v[10:13]
	v_mfma_f32_16x16x32_bf16 v[6:9], v[218:221], v[210:213], v[6:9]
	v_mfma_f32_16x16x32_bf16 v[2:5], v[226:229], v[210:213], v[2:5]
	s_add_i32 s49, 0, 0x18000
	v_add_u32_e32 v168, s49, v1
	s_barrier
	ds_read_b128 v[156:159], v168
	ds_read_b128 v[160:163], v168 offset:1024
	ds_read_b128 v[164:167], v168 offset:2048
	ds_read_b128 v[168:171], v168 offset:3072
	s_add_u32 s20, s24, 0xb0000
	s_addc_u32 s21, s25, 0
	s_mov_b32 m0, s29
	v_lshl_add_u64 v[214:215], s[20:21], 0, v[130:131]
	ds_read_b128 v[172:175], v155 offset:32768
	ds_read_b128 v[176:179], v155 offset:33792
	ds_read_b128 v[180:183], v155 offset:34816
	ds_read_b128 v[184:187], v155 offset:35840
	ds_read_b128 v[198:201], v155 offset:36864
	ds_read_b128 v[202:205], v155 offset:37888
	ds_read_b128 v[206:209], v155 offset:38912
	ds_read_b128 v[210:213], v155 offset:39936
	global_load_lds_dwordx4 v[214:215], off
	v_lshl_add_u64 v[214:215], s[20:21], 0, v[134:135]
	s_mov_b32 m0, s33
	s_nop 0
	global_load_lds_dwordx4 v[214:215], off
	s_waitcnt lgkmcnt(8)
	s_barrier
	s_waitcnt lgkmcnt(0)
	s_waitcnt lgkmcnt(0)
	v_mfma_f32_16x16x32_bf16 v[126:129], v[156:159], v[172:175], v[126:129]
	v_mfma_f32_16x16x32_bf16 v[122:125], v[164:167], v[172:175], v[122:125]
	v_mfma_f32_16x16x32_bf16 v[118:121], v[156:159], v[180:183], v[118:121]
	v_mfma_f32_16x16x32_bf16 v[110:113], v[164:167], v[180:183], v[110:113]
	v_mfma_f32_16x16x32_bf16 v[102:105], v[156:159], v[198:201], v[102:105]
	v_mfma_f32_16x16x32_bf16 v[94:97], v[164:167], v[198:201], v[94:97]
	v_mfma_f32_16x16x32_bf16 v[86:89], v[156:159], v[206:209], v[86:89]
	v_mfma_f32_16x16x32_bf16 v[78:81], v[164:167], v[206:209], v[78:81]
	v_mfma_f32_16x16x32_bf16 v[126:129], v[160:163], v[176:179], v[126:129]
	v_mfma_f32_16x16x32_bf16 v[122:125], v[168:171], v[176:179], v[122:125]
	v_mfma_f32_16x16x32_bf16 v[118:121], v[160:163], v[184:187], v[118:121]
	v_mfma_f32_16x16x32_bf16 v[110:113], v[168:171], v[184:187], v[110:113]
	v_mfma_f32_16x16x32_bf16 v[102:105], v[160:163], v[202:205], v[102:105]
	v_mfma_f32_16x16x32_bf16 v[94:97], v[168:171], v[202:205], v[94:97]
	v_mfma_f32_16x16x32_bf16 v[86:89], v[160:163], v[210:213], v[86:89]
	v_mfma_f32_16x16x32_bf16 v[78:81], v[168:171], v[210:213], v[78:81]
	s_barrier
	s_add_i32 s20, 0, 0x1c000
	s_add_i32 s21, s49, s26
	v_add_u32_e32 v226, s20, v1
	v_lshl_add_u64 v[152:153], v[152:153], 0, s[10:11]
	s_mov_b32 m0, s21
	ds_read_b128 v[214:217], v226
	ds_read_b128 v[218:221], v226 offset:1024
	ds_read_b128 v[222:225], v226 offset:2048
	ds_read_b128 v[226:229], v226 offset:3072
	global_load_lds_dwordx4 v[152:153], off
	v_lshl_add_u64 v[152:153], v[230:231], 0, s[10:11]
	s_add_i32 m0, s21, 0x2000
	s_nop 0
	global_load_lds_dwordx4 v[152:153], off
	s_barrier
	s_waitcnt lgkmcnt(0)
	s_waitcnt lgkmcnt(0)
	v_mfma_f32_16x16x32_bf16 v[114:117], v[214:217], v[172:175], v[114:117]
	v_mfma_f32_16x16x32_bf16 v[106:109], v[222:225], v[172:175], v[106:109]
	v_mfma_f32_16x16x32_bf16 v[98:101], v[214:217], v[180:183], v[98:101]
	v_mfma_f32_16x16x32_bf16 v[90:93], v[222:225], v[180:183], v[90:93]
	v_mfma_f32_16x16x32_bf16 v[82:85], v[214:217], v[198:201], v[82:85]
	v_mfma_f32_16x16x32_bf16 v[74:77], v[222:225], v[198:201], v[74:77]
	v_mfma_f32_16x16x32_bf16 v[70:73], v[214:217], v[206:209], v[70:73]
	v_mfma_f32_16x16x32_bf16 v[66:69], v[222:225], v[206:209], v[66:69]
	v_mfma_f32_16x16x32_bf16 v[114:117], v[218:221], v[176:179], v[114:117]
	v_mfma_f32_16x16x32_bf16 v[106:109], v[226:229], v[176:179], v[106:109]
	v_mfma_f32_16x16x32_bf16 v[98:101], v[218:221], v[184:187], v[98:101]
	v_mfma_f32_16x16x32_bf16 v[90:93], v[226:229], v[184:187], v[90:93]
	v_mfma_f32_16x16x32_bf16 v[82:85], v[218:221], v[202:205], v[82:85]
	v_mfma_f32_16x16x32_bf16 v[74:77], v[226:229], v[202:205], v[74:77]
	v_mfma_f32_16x16x32_bf16 v[70:73], v[218:221], v[210:213], v[70:73]
	v_mfma_f32_16x16x32_bf16 v[66:69], v[226:229], v[210:213], v[66:69]
	s_mov_b32 m0, s37
	v_lshl_add_u64 v[152:153], v[232:233], 0, s[10:11]
	s_barrier
	ds_read_b128 v[172:175], v155 offset:49152
	ds_read_b128 v[176:179], v155 offset:50176
	ds_read_b128 v[180:183], v155 offset:51200
	ds_read_b128 v[184:187], v155 offset:52224
	ds_read_b128 v[198:201], v155 offset:53248
	ds_read_b128 v[202:205], v155 offset:54272
	ds_read_b128 v[206:209], v155 offset:55296
	ds_read_b128 v[210:213], v155 offset:56320
	global_load_lds_dwordx4 v[152:153], off
	v_lshl_add_u64 v[152:153], v[234:235], 0, s[10:11]
	s_mov_b32 m0, s40
	s_nop 0
	global_load_lds_dwordx4 v[152:153], off
	s_barrier
; #define PG8_STAGE(bufoff, gbase, voff) do { _Pragma("unroll") for (int _i = 0; _i < 2; ++_i) \
;         __builtin_amdgcn_global_load_lds((const unsigned*)((const char*)(gbase) + (voff)[_i]), (LAS unsigned*)(lds + (bufoff) + ldsw + _i * 8192), 16, 0, 0); } while (0)
; #define PG8_MMA(ai, bj, At, Bt) do { __builtin_amdgcn_s_setprio(1); _Pragma("unroll") for (int m = 0; m < 4; ++m) _Pragma("unroll") for (int n = 0; n < 2; ++n) _Pragma("unroll") for (int k = 0; k < 2; ++k) \
;         acc[ai][bj][m][n] = __builtin_amdgcn_mfma_f32_16x16x32_bf16(Bt[n][k], At[m][k], acc[ai][bj][m][n], 0, 0, 0); __builtin_amdgcn_s_setprio(0); } while (0)
; #define PG8_WAIT_V(n) asm volatile("s_waitcnt vmcnt(" #n ")" ::: "memory")
; #define PG8_WAIT_L(n) asm volatile("s_waitcnt lgkmcnt(" #n ")" ::: "memory")
; #define PG8_BAR __builtin_amdgcn_s_barrier()
; #define PG8_SCHED __builtin_amdgcn_sched_barrier(0)
; template <class Epi>
; DEV void gemm_phase(LAS unsigned char* lds, const int tid, const Gemm g, const StaticOrder& S, const Epi& E) {
;     ...
;             PG8_BAR; PG8_WAIT_L(0); PG8_MMA(1, 0, At, B0); PG8_BAR; PG8_SCHED;
;             PG8_STAGE(PG8_SB(1, 1), b3 + hstep, voffB);
;             PG8_WAIT_V(6); PG8_BAR; PG8_MMA(1, 1, At, B1); PG8_BAR;
;         }
	s_waitcnt lgkmcnt(0)
	s_waitcnt lgkmcnt(0)
	v_mfma_f32_16x16x32_bf16 v[62:65], v[156:159], v[172:175], v[62:65]
	v_mfma_f32_16x16x32_bf16 v[58:61], v[164:167], v[172:175], v[58:61]
	v_mfma_f32_16x16x32_bf16 v[54:57], v[156:159], v[180:183], v[54:57]
	v_mfma_f32_16x16x32_bf16 v[46:49], v[164:167], v[180:183], v[46:49]
	v_mfma_f32_16x16x32_bf16 v[38:41], v[156:159], v[198:201], v[38:41]
	v_mfma_f32_16x16x32_bf16 v[30:33], v[164:167], v[198:201], v[30:33]
	v_mfma_f32_16x16x32_bf16 v[22:25], v[156:159], v[206:209], v[22:25]
	v_mfma_f32_16x16x32_bf16 v[14:17], v[164:167], v[206:209], v[14:17]
	v_mfma_f32_16x16x32_bf16 v[62:65], v[160:163], v[176:179], v[62:65]
	v_mfma_f32_16x16x32_bf16 v[58:61], v[168:171], v[176:179], v[58:61]
	v_mfma_f32_16x16x32_bf16 v[54:57], v[160:163], v[184:187], v[54:57]
	v_mfma_f32_16x16x32_bf16 v[46:49], v[168:171], v[184:187], v[46:49]
	v_mfma_f32_16x16x32_bf16 v[38:41], v[160:163], v[202:205], v[38:41]
	v_mfma_f32_16x16x32_bf16 v[30:33], v[168:171], v[202:205], v[30:33]
	v_mfma_f32_16x16x32_bf16 v[22:25], v[160:163], v[210:213], v[22:25]
	v_mfma_f32_16x16x32_bf16 v[14:17], v[168:171], v[210:213], v[14:17]
	s_barrier
	s_add_u32 s6, s6, 0xb0080
	s_addc_u32 s7, s7, 0
	s_add_i32 s20, s20, s26
	v_lshl_add_u64 v[152:153], s[6:7], 0, v[132:133]
	s_mov_b32 m0, s20
	s_nop 0
	global_load_lds_dwordx4 v[152:153], off
	v_lshl_add_u64 v[152:153], s[6:7], 0, v[136:137]
	s_add_i32 m0, s20, 0x2000
	s_nop 0
	global_load_lds_dwordx4 v[152:153], off
	s_waitcnt vmcnt(6)
	s_barrier
	v_mfma_f32_16x16x32_bf16 v[50:53], v[214:217], v[172:175], v[50:53]
	v_mfma_f32_16x16x32_bf16 v[42:45], v[222:225], v[172:175], v[42:45]
	v_mfma_f32_16x16x32_bf16 v[34:37], v[214:217], v[180:183], v[34:37]
	v_mfma_f32_16x16x32_bf16 v[26:29], v[222:225], v[180:183], v[26:29]
	v_mfma_f32_16x16x32_bf16 v[18:21], v[214:217], v[198:201], v[18:21]
	v_mfma_f32_16x16x32_bf16 v[10:13], v[222:225], v[198:201], v[10:13]
	v_mfma_f32_16x16x32_bf16 v[6:9], v[214:217], v[206:209], v[6:9]
	v_mfma_f32_16x16x32_bf16 v[2:5], v[222:225], v[206:209], v[2:5]
	v_mfma_f32_16x16x32_bf16 v[50:53], v[218:221], v[176:179], v[50:53]
	v_mfma_f32_16x16x32_bf16 v[42:45], v[226:229], v[176:179], v[42:45]
	v_mfma_f32_16x16x32_bf16 v[34:37], v[218:221], v[184:187], v[34:37]
	v_mfma_f32_16x16x32_bf16 v[26:29], v[226:229], v[184:187], v[26:29]
	v_mfma_f32_16x16x32_bf16 v[18:21], v[218:221], v[202:205], v[18:21]
	v_mfma_f32_16x16x32_bf16 v[10:13], v[226:229], v[202:205], v[10:13]
	v_mfma_f32_16x16x32_bf16 v[6:9], v[218:221], v[210:213], v[6:9]
	v_mfma_f32_16x16x32_bf16 v[2:5], v[226:229], v[210:213], v[2:5]
	s_setprio 0
	s_add_i32 s48, s48, 2
	s_add_u32 s46, s46, 0x100
	s_addc_u32 s47, s47, 0
	s_cmp_gt_u32 s48, 41
	s_mov_b64 s[20:21], s[22:23]
	s_barrier
	s_cbranch_scc0 .LBB0_1374
; DEV unsigned cvt_pk_bf16(float lo, float hi) { unsigned r; asm volatile("v_cvt_pk_bf16_f32 %0, %1, %2" : "=v"(r) : "v"(lo), "v"(hi)); return r; }
;     DEV void operator()(const f32x4 (&acc)[2][2][4][2], const Unit& u, int wr, int wc, int fr, int fq) const {
;         const int row0 = prow(u.pm) + wr * 64 + fr; const int col0 = u.pn * BM + wc * 32 + 8 * fq;
; #pragma unroll
;         for (int ai = 0; ai < 2; ++ai)
; #pragma unroll
;             for (int m = 0; m < 4; ++m) { bf16_t* rowp = O + (size_t)(row0 + ai * HALF + m * 16) * ldc + col0;
; #pragma unroll
;                 for (int bj = 0; bj < 2; ++bj) { const f32x4 v0 = acc[ai][bj][m][0], v1 = acc[ai][bj][m][1];
;                     u32x4 w; w.x = cvt_pk_bf16(v0[0], v0[1]); w.y = cvt_pk_bf16(v0[2], v0[3]); w.z = cvt_pk_bf16(v1[0], v1[1]); w.w = cvt_pk_bf16(v1[2], v1[3]);
;                     *(u32x4*)(rowp + bj * HALF) = w; } }
;     }
; template <class Epi>
; DEV void gemm_phase(LAS unsigned char* lds, const int tid, const Gemm g, const StaticOrder& S, const Epi& E) {
;     ...
;         E(acc, cur, wr, wc, fr, fq);
;         if (!has_next) break;
; #pragma unroll
;         for (int a = 0; a < 2; ++a)
; #pragma unroll
;             for (int b = 0; b < 2; ++b)
; #pragma unroll
;                 for (int m = 0; m < 4; ++m)
; #pragma unroll
;                     for (int n = 0; n < 2; ++n) acc[a][b][m][n] = (f32x4){0.f, 0.f, 0.f, 0.f};
;         cur = nxt; cA = nA; cB = nB; ++ui;
;     }
	s_lshl_b32 s7, s43, 2
	s_lshl_b32 s6, s43, 8
	s_and_b32 s7, s7, 0xffffff00
	s_add_i32 s7, s7, s6
	v_add_u32_e32 v156, s7, v141
	v_lshl_or_b32 v152, s42, 8, v154
	v_ashrrev_i32_e32 v157, 31, v156
	v_ashrrev_i32_e32 v153, 31, v152
	v_lshlrev_b64 v[158:159], 11, v[156:157]
	v_lshl_add_u64 v[158:159], s[12:13], 0, v[158:159]
	v_lshlrev_b64 v[160:161], 1, v[152:153]
	v_lshl_add_u64 v[152:153], v[158:159], 0, v[160:161]
	v_cvt_pk_bf16_f32 v126, v126, v127
	v_cvt_pk_bf16_f32 v127, v128, v129
	v_cvt_pk_bf16_f32 v128, v122, v123
	v_cvt_pk_bf16_f32 v129, v124, v125
	global_store_dwordx4 v[152:153], v[126:129], off
	v_cvt_pk_bf16_f32 v114, v114, v115
	v_cvt_pk_bf16_f32 v115, v116, v117
	v_cvt_pk_bf16_f32 v116, v106, v107
	v_or_b32_e32 v106, 16, v156
	v_ashrrev_i32_e32 v107, 31, v106
	v_lshlrev_b64 v[106:107], 11, v[106:107]
	v_lshl_add_u64 v[106:107], s[12:13], 0, v[106:107]
	v_cvt_pk_bf16_f32 v117, v108, v109
	global_store_dwordx4 v[152:153], v[114:117], off offset:256
	s_mov_b64 s[6:7], 0x40000
	s_mov_b32 s42, s45
	v_lshl_add_u64 v[114:115], v[106:107], 0, v[160:161]
	v_cvt_pk_bf16_f32 v106, v118, v119
	v_cvt_pk_bf16_f32 v107, v120, v121
	v_cvt_pk_bf16_f32 v108, v110, v111
	v_cvt_pk_bf16_f32 v109, v112, v113
	global_store_dwordx4 v[114:115], v[106:109], off
	v_cvt_pk_bf16_f32 v98, v98, v99
	v_cvt_pk_bf16_f32 v99, v100, v101
	v_cvt_pk_bf16_f32 v100, v90, v91
	v_or_b32_e32 v90, 32, v156
	v_ashrrev_i32_e32 v91, 31, v90
	v_lshlrev_b64 v[90:91], 11, v[90:91]
	v_lshl_add_u64 v[90:91], s[12:13], 0, v[90:91]
	v_cvt_pk_bf16_f32 v101, v92, v93
	global_store_dwordx4 v[114:115], v[98:101], off offset:256
	s_mov_b32 s43, s44
	s_mov_b32 s24, s45
	v_lshl_add_u64 v[98:99], v[90:91], 0, v[160:161]
	v_cvt_pk_bf16_f32 v90, v102, v103
	v_cvt_pk_bf16_f32 v91, v104, v105
	v_cvt_pk_bf16_f32 v92, v94, v95
	v_cvt_pk_bf16_f32 v93, v96, v97
	global_store_dwordx4 v[98:99], v[90:93], off
	v_cvt_pk_bf16_f32 v82, v82, v83
	v_cvt_pk_bf16_f32 v83, v84, v85
	v_cvt_pk_bf16_f32 v84, v74, v75
	v_or_b32_e32 v74, 48, v156
	v_ashrrev_i32_e32 v75, 31, v74
	v_lshlrev_b64 v[74:75], 11, v[74:75]
	v_lshl_add_u64 v[74:75], s[12:13], 0, v[74:75]
	v_cvt_pk_bf16_f32 v85, v76, v77
	global_store_dwordx4 v[98:99], v[82:85], off offset:256
	s_mov_b32 s25, s44
	s_mov_b64 s[22:23], s[18:19]
	v_lshl_add_u64 v[82:83], v[74:75], 0, v[160:161]
	v_cvt_pk_bf16_f32 v74, v86, v87
	v_cvt_pk_bf16_f32 v75, v88, v89
	v_cvt_pk_bf16_f32 v76, v78, v79
	v_cvt_pk_bf16_f32 v77, v80, v81
	global_store_dwordx4 v[82:83], v[74:77], off
	v_cvt_pk_bf16_f32 v70, v70, v71
	v_cvt_pk_bf16_f32 v71, v72, v73
	v_cvt_pk_bf16_f32 v72, v66, v67
	v_lshl_add_u64 v[66:67], v[152:153], 0, s[6:7]
	s_mov_b32 s6, 0x40000
	v_cvt_pk_bf16_f32 v73, v68, v69
	global_store_dwordx4 v[82:83], v[70:73], off offset:256
	v_cvt_pk_bf16_f32 v62, v62, v63
	v_cvt_pk_bf16_f32 v63, v64, v65
	v_cvt_pk_bf16_f32 v64, v58, v59
	v_add_co_u32_e32 v58, vcc, s6, v152
	v_cvt_pk_bf16_f32 v65, v60, v61
	s_mov_b64 s[6:7], 0x48000
	s_nop 0
	v_addc_co_u32_e32 v59, vcc, 0, v153, vcc
	global_store_dwordx4 v[58:59], v[62:65], off
	v_cvt_pk_bf16_f32 v50, v50, v51
	v_cvt_pk_bf16_f32 v51, v52, v53
	v_cvt_pk_bf16_f32 v52, v42, v43
	v_cvt_pk_bf16_f32 v53, v44, v45
	global_store_dwordx4 v[66:67], v[50:53], off offset:256
	v_cvt_pk_bf16_f32 v42, v54, v55
	v_cvt_pk_bf16_f32 v43, v56, v57
	v_cvt_pk_bf16_f32 v44, v46, v47
	v_cvt_pk_bf16_f32 v45, v48, v49
	s_mov_b64 s[20:21], s[2:3]
	s_nop 0
	v_lshl_add_u64 v[50:51], v[152:153], 0, s[6:7]
	s_mov_b32 s6, 0x48000
	v_add_co_u32_e32 v46, vcc, s6, v152
	s_mov_b64 s[6:7], 0x50000
	s_nop 0
	v_addc_co_u32_e32 v47, vcc, 0, v153, vcc
	global_store_dwordx4 v[46:47], v[42:45], off
	v_cvt_pk_bf16_f32 v34, v34, v35
	v_cvt_pk_bf16_f32 v35, v36, v37
	v_cvt_pk_bf16_f32 v36, v26, v27
	v_cvt_pk_bf16_f32 v37, v28, v29
	global_store_dwordx4 v[50:51], v[34:37], off offset:256
	v_cvt_pk_bf16_f32 v26, v38, v39
	v_cvt_pk_bf16_f32 v27, v40, v41
	v_cvt_pk_bf16_f32 v28, v30, v31
	v_cvt_pk_bf16_f32 v29, v32, v33
	s_nop 1
	v_lshl_add_u64 v[34:35], v[152:153], 0, s[6:7]
	s_mov_b32 s6, 0x50000
	v_add_co_u32_e32 v30, vcc, s6, v152
	s_mov_b64 s[6:7], 0x58000
	s_nop 0
	v_addc_co_u32_e32 v31, vcc, 0, v153, vcc
	global_store_dwordx4 v[30:31], v[26:29], off
	v_cvt_pk_bf16_f32 v18, v18, v19
	v_cvt_pk_bf16_f32 v19, v20, v21
	v_cvt_pk_bf16_f32 v20, v10, v11
	v_cvt_pk_bf16_f32 v21, v12, v13
	global_store_dwordx4 v[34:35], v[18:21], off offset:256
	v_cvt_pk_bf16_f32 v10, v22, v23
	v_cvt_pk_bf16_f32 v11, v24, v25
	v_cvt_pk_bf16_f32 v12, v14, v15
	v_cvt_pk_bf16_f32 v13, v16, v17
	s_nop 1
	v_lshl_add_u64 v[18:19], v[152:153], 0, s[6:7]
	s_mov_b32 s6, 0x58000
	v_add_co_u32_e32 v14, vcc, s6, v152
	s_nop 1
	v_addc_co_u32_e32 v15, vcc, 0, v153, vcc
	s_and_b64 vcc, exec, s[0:1]
	global_store_dwordx4 v[14:15], v[10:13], off
	v_cvt_pk_bf16_f32 v6, v6, v7
	v_cvt_pk_bf16_f32 v7, v8, v9
	v_cvt_pk_bf16_f32 v8, v2, v3
	v_cvt_pk_bf16_f32 v9, v4, v5
	global_store_dwordx4 v[18:19], v[6:9], off offset:256
	s_cbranch_vccz .LBB0_1360
	s_branch .LBB0_1378
